# v43 plus: LDS read base addresses of the A half-tile buffers formed once per unit in persistent VGPRs (no VALU left in the K-loop load segments)
# speedup vs baseline: 1.0083x; 1.0083x over previous
; #define PG8_STAGE(bufoff, gbase, voff) do { _Pragma("unroll") for (int _i = 0; _i < 2; ++_i) \
;         __builtin_amdgcn_global_load_lds((const unsigned*)((const char*)(gbase) + (voff)[_i]), (PG8_LAS unsigned*)(lds + (bufoff) + ldsw + _i * 8192), 16, 0, 0); } while (0)
; #define PG8_LDA(dst, b, h) do { _Pragma("unroll") for (int m = 0; m < 4; ++m) _Pragma("unroll") for (int k = 0; k < 2; ++k) dst[m][k] = *(const PG8_LAS bf16x8*)(lds + PG8_SA(b, h) + aoff + m * 2048 + k * 1024); } while (0)
; #define PG8_LDB(dst, b, h) do { _Pragma("unroll") for (int n = 0; n < 2; ++n) _Pragma("unroll") for (int k = 0; k < 2; ++k) dst[n][k] = *(const PG8_LAS bf16x8*)(lds + PG8_SB(b, h) + boff + n * 2048 + k * 1024); } while (0)
; #define PG8_WAIT_V(n) asm volatile("s_waitcnt vmcnt(" #n ")" ::: "memory")
; #define PG8_WAIT_L(n) asm volatile("s_waitcnt lgkmcnt(" #n ")" ::: "memory")
; #define PG8_BAR __builtin_amdgcn_s_barrier()
; #define PG8_SCHED __builtin_amdgcn_sched_barrier(0)
; template <class Epi, class Sched, bool ALIGN_EPI = false, bool SP2 = false>
; __device__ __forceinline__ void gemm_phase(PG8_LAS unsigned char* lds, const Gemm g, const Sched& S, const Epi& E) {
;     ...
;         const bool has_next = S.next(ui + 1, nxt);
;         const char* nA = has_next ? (const char*)g.A + (size_t)nxt.pm * tstep : cA; const char* nB = has_next ? (const char*)g.Bt + (size_t)nxt.pn * tstep : cB;
;         for (int t = 0; t < nt; t += 2) {
;             const bool last = (t == nt - 2);
;             const char* a1 = cA + (size_t)(t + 1) * kstep;
;             const char* a2 = last ? nA : cA + (size_t)(t + 2) * kstep; const char* b2 = last ? nB : cB + (size_t)(t + 2) * kstep;
;             const char* a3 = a2 + kstep; const char* b3 = b2 + kstep;
;             if (last && has_next) S.a_ready(nxt);
;             if constexpr (SP2) {
;             PG8_LDB(B0, 0, 0); PG8_LDB(B1, 0, 1); PG8_SCHED; PG8_LDA(At, 0, 0); PG8_STAGE(PG8_SA(1, 1), a1 + hstep, voffA);
;             PG8_WAIT_V(8); PG8_WAIT_L(0); PG8_BAR; PG8_MMA(0, 0, At, B0); PG8_MMA(0, 1, At, B1); PG8_BAR; PG8_SCHED;
;             PG8_LDA(At, 0, 1); PG8_STAGE(PG8_SB(0, 0), b2, voffB); PG8_STAGE(PG8_SB(0, 1), b2 + hstepB, voffB); PG8_STAGE(PG8_SA(0, 0), a2, voffA);
;             PG8_WAIT_V(8); PG8_WAIT_L(0); PG8_BAR; PG8_MMA(1, 0, At, B0); PG8_MMA(1, 1, At, B1); PG8_BAR; PG8_SCHED;
.LBB0_169:
	s_add_u32 s93, s46, 0x100
	s_addc_u32 s94, s47, 0
	s_ashr_i32 s69, s68, 31
	s_lshl_b64 s[4:5], s[68:69], 20
	s_add_u32 s76, s52, s4
	s_addc_u32 s77, s53, s5
	s_and_b64 s[4:5], s[38:39], exec
	s_cselect_b32 s4, s77, s71
	s_cselect_b32 s5, s76, s70
	s_ashr_i32 s63, s62, 31
	s_lshl_b64 s[6:7], s[62:63], 20
	v_readlane_b32 s8, v249, 19
	v_readlane_b32 s9, v249, 20
	s_add_u32 s72, s8, s6
	s_addc_u32 s73, s9, s7
	s_and_b64 s[6:7], s[38:39], exec
	s_cselect_b32 s6, s73, s47
	s_cselect_b32 s7, s72, s46
	s_add_u32 s8, s70, 0x80080
	s_addc_u32 s9, s71, 0
	v_lshl_add_u64 v[144:145], s[8:9], 0, v[140:141]
	v_lshl_add_u64 v[146:147], s[8:9], 0, v[142:143]
	s_mov_b32 s8, -2
	s_mov_b64 s[46:47], 0
	v_add_u32_e32 v186, 0x10000, v139
	v_add_u32_e32 v187, 0x14000, v139
	v_add_u32_e32 v198, 0x18000, v139
	v_add_u32_e32 v199, 0x1c000, v139
.LBB0_170:
	s_add_u32 s9, s70, s46
	s_addc_u32 s10, s71, s47
	s_add_u32 s9, s9, 0x100
	s_addc_u32 s10, s10, 0
	s_add_u32 s100, s9, 0x7ff80
	s_addc_u32 s101, s10, 0
	s_add_u32 s11, s93, s46
	s_addc_u32 s12, s94, s47
	s_add_i32 s13, 0, 0x10000
	s_cmpk_eq_i32 s46, 0xf00
	s_cselect_b32 s85, s4, s10
	s_cselect_b32 s84, s5, s9
	s_cselect_b32 s81, s6, s12
	s_cselect_b32 s80, s7, s11
	s_add_i32 s9, 0, 0x14000
	ds_read_b128 v[148:151], v186
	ds_read_b128 v[152:155], v186 offset:1024
	ds_read_b128 v[156:159], v186 offset:2048
	ds_read_b128 v[160:163], v186 offset:3072
	ds_read_b128 v[166:169], v187
	ds_read_b128 v[170:173], v187 offset:1024
	ds_read_b128 v[174:177], v187 offset:2048
	ds_read_b128 v[178:181], v187 offset:3072
	s_add_i32 m0, s1, 0xc000
	ds_read_b128 v[182:185], v165
	ds_read_b128 v[206:209], v165 offset:1024
	ds_read_b128 v[210:213], v165 offset:2048
	ds_read_b128 v[214:217], v165 offset:3072
	ds_read_b128 v[218:221], v165 offset:4096
	ds_read_b128 v[236:239], v165 offset:5120
	ds_read_b128 v[240:243], v165 offset:6144
	ds_read_b128 v[244:247], v165 offset:7168
	global_load_lds_dwordx4 v140, s[100:101]
	s_add_i32 m0, s1, 0xe000
	s_nop 0
	global_load_lds_dwordx4 v142, s[100:101]
	s_waitcnt vmcnt(8)
	s_waitcnt lgkmcnt(0)
	s_barrier
	v_mfma_f32_16x16x32_bf16 v[126:129], v[148:151], v[182:185], v[126:129]
	v_mfma_f32_16x16x32_bf16 v[122:125], v[156:159], v[182:185], v[122:125]
	v_mfma_f32_16x16x32_bf16 v[118:121], v[148:151], v[210:213], v[118:121]
	v_mfma_f32_16x16x32_bf16 v[114:117], v[156:159], v[210:213], v[114:117]
	v_mfma_f32_16x16x32_bf16 v[110:113], v[148:151], v[218:221], v[110:113]
	v_mfma_f32_16x16x32_bf16 v[106:109], v[156:159], v[218:221], v[106:109]
	v_mfma_f32_16x16x32_bf16 v[102:105], v[148:151], v[240:243], v[102:105]
	v_mfma_f32_16x16x32_bf16 v[98:101], v[156:159], v[240:243], v[98:101]
	v_mfma_f32_16x16x32_bf16 v[126:129], v[152:155], v[206:209], v[126:129]
	v_mfma_f32_16x16x32_bf16 v[122:125], v[160:163], v[206:209], v[122:125]
	v_mfma_f32_16x16x32_bf16 v[118:121], v[152:155], v[214:217], v[118:121]
	v_mfma_f32_16x16x32_bf16 v[114:117], v[160:163], v[214:217], v[114:117]
	v_mfma_f32_16x16x32_bf16 v[110:113], v[152:155], v[236:239], v[110:113]
	v_mfma_f32_16x16x32_bf16 v[106:109], v[160:163], v[236:239], v[106:109]
	v_mfma_f32_16x16x32_bf16 v[102:105], v[152:155], v[244:247], v[102:105]
	v_mfma_f32_16x16x32_bf16 v[98:101], v[160:163], v[244:247], v[98:101]
	v_mfma_f32_16x16x32_bf16 v[94:97], v[166:169], v[182:185], v[94:97]
	v_mfma_f32_16x16x32_bf16 v[90:93], v[174:177], v[182:185], v[90:93]
	v_mfma_f32_16x16x32_bf16 v[86:89], v[166:169], v[210:213], v[86:89]
	v_mfma_f32_16x16x32_bf16 v[82:85], v[174:177], v[210:213], v[82:85]
	v_mfma_f32_16x16x32_bf16 v[78:81], v[166:169], v[218:221], v[78:81]
	v_mfma_f32_16x16x32_bf16 v[74:77], v[174:177], v[218:221], v[74:77]
	v_mfma_f32_16x16x32_bf16 v[70:73], v[166:169], v[240:243], v[70:73]
	v_mfma_f32_16x16x32_bf16 v[66:69], v[174:177], v[240:243], v[66:69]
	v_mfma_f32_16x16x32_bf16 v[94:97], v[170:173], v[206:209], v[94:97]
	v_mfma_f32_16x16x32_bf16 v[90:93], v[178:181], v[206:209], v[90:93]
	v_mfma_f32_16x16x32_bf16 v[86:89], v[170:173], v[214:217], v[86:89]
	v_mfma_f32_16x16x32_bf16 v[82:85], v[178:181], v[214:217], v[82:85]
	v_mfma_f32_16x16x32_bf16 v[78:81], v[170:173], v[236:239], v[78:81]
	v_mfma_f32_16x16x32_bf16 v[74:77], v[178:181], v[236:239], v[74:77]
	v_mfma_f32_16x16x32_bf16 v[70:73], v[170:173], v[244:247], v[70:73]
	v_mfma_f32_16x16x32_bf16 v[66:69], v[178:181], v[244:247], v[66:69]
	s_barrier
	s_add_i32 s10, s13, s0
	s_mov_b32 m0, s10
	ds_read_b128 v[182:185], v165 offset:16384
	ds_read_b128 v[206:209], v165 offset:17408
	ds_read_b128 v[210:213], v165 offset:18432
	ds_read_b128 v[214:217], v165 offset:19456
	ds_read_b128 v[218:221], v165 offset:20480
	ds_read_b128 v[236:239], v165 offset:21504
	ds_read_b128 v[240:243], v165 offset:22528
	ds_read_b128 v[244:247], v165 offset:23552
	global_load_lds_dwordx4 v132, s[80:81]
	s_add_i32 m0, s10, 0x2000
	s_add_u32 s10, s80, 0x20000
	s_addc_u32 s11, s81, 0
	s_add_i32 s9, s9, s0
	global_load_lds_dwordx4 v136, s[80:81]
	s_mov_b32 m0, s9
	s_nop 0
	global_load_lds_dwordx4 v132, s[10:11]
	s_add_i32 m0, s9, 0x2000
	s_nop 0
	global_load_lds_dwordx4 v136, s[10:11]
	s_mov_b32 m0, s1
	s_nop 0
	global_load_lds_dwordx4 v130, s[84:85]
	s_mov_b32 m0, s25
	s_nop 0
	global_load_lds_dwordx4 v134, s[84:85]
	s_waitcnt vmcnt(8)
	s_waitcnt lgkmcnt(0)
	s_barrier
; #define PG8_STAGE(bufoff, gbase, voff) do { _Pragma("unroll") for (int _i = 0; _i < 2; ++_i) \
;         __builtin_amdgcn_global_load_lds((const unsigned*)((const char*)(gbase) + (voff)[_i]), (PG8_LAS unsigned*)(lds + (bufoff) + ldsw + _i * 8192), 16, 0, 0); } while (0)
; #define PG8_LDA(dst, b, h) do { _Pragma("unroll") for (int m = 0; m < 4; ++m) _Pragma("unroll") for (int k = 0; k < 2; ++k) dst[m][k] = *(const PG8_LAS bf16x8*)(lds + PG8_SA(b, h) + aoff + m * 2048 + k * 1024); } while (0)
; #define PG8_LDB(dst, b, h) do { _Pragma("unroll") for (int n = 0; n < 2; ++n) _Pragma("unroll") for (int k = 0; k < 2; ++k) dst[n][k] = *(const PG8_LAS bf16x8*)(lds + PG8_SB(b, h) + boff + n * 2048 + k * 1024); } while (0)
; #define PG8_MMA(ai, bj, At, Bt) do { __builtin_amdgcn_s_setprio(1); _Pragma("unroll") for (int m = 0; m < 4; ++m) _Pragma("unroll") for (int n = 0; n < 2; ++n) _Pragma("unroll") for (int k = 0; k < 2; ++k) \
;         acc[ai][bj][m][n] = __builtin_amdgcn_mfma_f32_16x16x32_bf16(Bt[n][k], At[m][k], acc[ai][bj][m][n], 0, 0, 0); __builtin_amdgcn_s_setprio(0); } while (0)
; #define PG8_WAIT_V(n) asm volatile("s_waitcnt vmcnt(" #n ")" ::: "memory")
; #define PG8_WAIT_L(n) asm volatile("s_waitcnt lgkmcnt(" #n ")" ::: "memory")
; #define PG8_BAR __builtin_amdgcn_s_barrier()
; #define PG8_SCHED __builtin_amdgcn_sched_barrier(0)
; template <class Epi, class Sched, bool ALIGN_EPI = false, bool SP2 = false>
; __device__ __forceinline__ void gemm_phase(PG8_LAS unsigned char* lds, const Gemm g, const Sched& S, const Epi& E) {
;     ...
;             PG8_WAIT_V(8); PG8_WAIT_L(0); PG8_BAR; PG8_MMA(1, 0, At, B0); PG8_MMA(1, 1, At, B1); PG8_BAR; PG8_SCHED;
;             PG8_LDB(B0, 1, 0); PG8_LDB(B1, 1, 1); PG8_SCHED; PG8_LDA(At, 1, 0); PG8_STAGE(PG8_SA(0, 1), a2 + hstep, voffA);
;             PG8_WAIT_V(8); PG8_WAIT_L(0); PG8_BAR; PG8_MMA(0, 0, At, B0); PG8_MMA(0, 1, At, B1); PG8_BAR; PG8_SCHED;
	v_mfma_f32_16x16x32_bf16 v[62:65], v[148:151], v[182:185], v[62:65]
	v_mfma_f32_16x16x32_bf16 v[58:61], v[156:159], v[182:185], v[58:61]
	v_mfma_f32_16x16x32_bf16 v[54:57], v[148:151], v[210:213], v[54:57]
	v_mfma_f32_16x16x32_bf16 v[50:53], v[156:159], v[210:213], v[50:53]
	v_mfma_f32_16x16x32_bf16 v[46:49], v[148:151], v[218:221], v[46:49]
	v_mfma_f32_16x16x32_bf16 v[42:45], v[156:159], v[218:221], v[42:45]
	v_mfma_f32_16x16x32_bf16 v[38:41], v[148:151], v[240:243], v[38:41]
	v_mfma_f32_16x16x32_bf16 v[34:37], v[156:159], v[240:243], v[34:37]
	v_mfma_f32_16x16x32_bf16 v[62:65], v[152:155], v[206:209], v[62:65]
	v_mfma_f32_16x16x32_bf16 v[58:61], v[160:163], v[206:209], v[58:61]
	v_mfma_f32_16x16x32_bf16 v[54:57], v[152:155], v[214:217], v[54:57]
	v_mfma_f32_16x16x32_bf16 v[50:53], v[160:163], v[214:217], v[50:53]
	v_mfma_f32_16x16x32_bf16 v[46:49], v[152:155], v[236:239], v[46:49]
	v_mfma_f32_16x16x32_bf16 v[42:45], v[160:163], v[236:239], v[42:45]
	v_mfma_f32_16x16x32_bf16 v[38:41], v[152:155], v[244:247], v[38:41]
	v_mfma_f32_16x16x32_bf16 v[34:37], v[160:163], v[244:247], v[34:37]
	v_mfma_f32_16x16x32_bf16 v[30:33], v[166:169], v[182:185], v[30:33]
	v_mfma_f32_16x16x32_bf16 v[26:29], v[174:177], v[182:185], v[26:29]
	v_mfma_f32_16x16x32_bf16 v[22:25], v[166:169], v[210:213], v[22:25]
	v_mfma_f32_16x16x32_bf16 v[18:21], v[174:177], v[210:213], v[18:21]
	v_mfma_f32_16x16x32_bf16 v[14:17], v[166:169], v[218:221], v[14:17]
	v_mfma_f32_16x16x32_bf16 v[10:13], v[174:177], v[218:221], v[10:13]
	v_mfma_f32_16x16x32_bf16 v[6:9], v[166:169], v[240:243], v[6:9]
	v_mfma_f32_16x16x32_bf16 v[2:5], v[174:177], v[240:243], v[2:5]
	v_mfma_f32_16x16x32_bf16 v[30:33], v[170:173], v[206:209], v[30:33]
	v_mfma_f32_16x16x32_bf16 v[26:29], v[178:181], v[206:209], v[26:29]
	v_mfma_f32_16x16x32_bf16 v[22:25], v[170:173], v[214:217], v[22:25]
	v_mfma_f32_16x16x32_bf16 v[18:21], v[178:181], v[214:217], v[18:21]
	v_mfma_f32_16x16x32_bf16 v[14:17], v[170:173], v[236:239], v[14:17]
	v_mfma_f32_16x16x32_bf16 v[10:13], v[178:181], v[236:239], v[10:13]
	v_mfma_f32_16x16x32_bf16 v[6:9], v[170:173], v[244:247], v[6:9]
	v_mfma_f32_16x16x32_bf16 v[2:5], v[178:181], v[244:247], v[2:5]
	s_barrier
	s_add_i32 s9, 0, 0x18000
	s_add_i32 s12, 0, 0x1c000
	ds_read_b128 v[148:151], v198
	ds_read_b128 v[152:155], v198 offset:1024
	ds_read_b128 v[156:159], v198 offset:2048
	ds_read_b128 v[160:163], v198 offset:3072
	ds_read_b128 v[166:169], v199
	ds_read_b128 v[170:173], v199 offset:1024
	ds_read_b128 v[174:177], v199 offset:2048
	ds_read_b128 v[178:181], v199 offset:3072
	s_add_u32 s10, s84, 0x80000
	s_addc_u32 s11, s85, 0
	s_mov_b32 m0, s42
	ds_read_b128 v[182:185], v165 offset:32768
	ds_read_b128 v[206:209], v165 offset:33792
	ds_read_b128 v[210:213], v165 offset:34816
	ds_read_b128 v[214:217], v165 offset:35840
	ds_read_b128 v[218:221], v165 offset:36864
	ds_read_b128 v[236:239], v165 offset:37888
	ds_read_b128 v[240:243], v165 offset:38912
	ds_read_b128 v[244:247], v165 offset:39936
	global_load_lds_dwordx4 v130, s[10:11]
	s_mov_b32 m0, s51
	s_nop 0
	global_load_lds_dwordx4 v134, s[10:11]
	s_waitcnt vmcnt(8)
	s_waitcnt lgkmcnt(0)
	s_barrier
	v_mfma_f32_16x16x32_bf16 v[126:129], v[148:151], v[182:185], v[126:129]
	v_mfma_f32_16x16x32_bf16 v[122:125], v[156:159], v[182:185], v[122:125]
	v_mfma_f32_16x16x32_bf16 v[118:121], v[148:151], v[210:213], v[118:121]
	v_mfma_f32_16x16x32_bf16 v[114:117], v[156:159], v[210:213], v[114:117]
	v_mfma_f32_16x16x32_bf16 v[110:113], v[148:151], v[218:221], v[110:113]
	v_mfma_f32_16x16x32_bf16 v[106:109], v[156:159], v[218:221], v[106:109]
	v_mfma_f32_16x16x32_bf16 v[102:105], v[148:151], v[240:243], v[102:105]
	v_mfma_f32_16x16x32_bf16 v[98:101], v[156:159], v[240:243], v[98:101]
	v_mfma_f32_16x16x32_bf16 v[126:129], v[152:155], v[206:209], v[126:129]
	v_mfma_f32_16x16x32_bf16 v[122:125], v[160:163], v[206:209], v[122:125]
	v_mfma_f32_16x16x32_bf16 v[118:121], v[152:155], v[214:217], v[118:121]
	v_mfma_f32_16x16x32_bf16 v[114:117], v[160:163], v[214:217], v[114:117]
	v_mfma_f32_16x16x32_bf16 v[110:113], v[152:155], v[236:239], v[110:113]
	v_mfma_f32_16x16x32_bf16 v[106:109], v[160:163], v[236:239], v[106:109]
	v_mfma_f32_16x16x32_bf16 v[102:105], v[152:155], v[244:247], v[102:105]
	v_mfma_f32_16x16x32_bf16 v[98:101], v[160:163], v[244:247], v[98:101]
	v_mfma_f32_16x16x32_bf16 v[94:97], v[166:169], v[182:185], v[94:97]
	v_mfma_f32_16x16x32_bf16 v[90:93], v[174:177], v[182:185], v[90:93]
	v_mfma_f32_16x16x32_bf16 v[86:89], v[166:169], v[210:213], v[86:89]
	v_mfma_f32_16x16x32_bf16 v[82:85], v[174:177], v[210:213], v[82:85]
	v_mfma_f32_16x16x32_bf16 v[78:81], v[166:169], v[218:221], v[78:81]
	v_mfma_f32_16x16x32_bf16 v[74:77], v[174:177], v[218:221], v[74:77]
	v_mfma_f32_16x16x32_bf16 v[70:73], v[166:169], v[240:243], v[70:73]
	v_mfma_f32_16x16x32_bf16 v[66:69], v[174:177], v[240:243], v[66:69]
	v_mfma_f32_16x16x32_bf16 v[94:97], v[170:173], v[206:209], v[94:97]
	v_mfma_f32_16x16x32_bf16 v[90:93], v[178:181], v[206:209], v[90:93]
	v_mfma_f32_16x16x32_bf16 v[86:89], v[170:173], v[214:217], v[86:89]
	v_mfma_f32_16x16x32_bf16 v[82:85], v[178:181], v[214:217], v[82:85]
	v_mfma_f32_16x16x32_bf16 v[78:81], v[170:173], v[236:239], v[78:81]
	v_mfma_f32_16x16x32_bf16 v[74:77], v[178:181], v[236:239], v[74:77]
	v_mfma_f32_16x16x32_bf16 v[70:73], v[170:173], v[244:247], v[70:73]
	v_mfma_f32_16x16x32_bf16 v[66:69], v[178:181], v[244:247], v[66:69]
	s_barrier
; #define PG8_STAGE(bufoff, gbase, voff) do { _Pragma("unroll") for (int _i = 0; _i < 2; ++_i) \
;         __builtin_amdgcn_global_load_lds((const unsigned*)((const char*)(gbase) + (voff)[_i]), (PG8_LAS unsigned*)(lds + (bufoff) + ldsw + _i * 8192), 16, 0, 0); } while (0)
; #define PG8_LDA(dst, b, h) do { _Pragma("unroll") for (int m = 0; m < 4; ++m) _Pragma("unroll") for (int k = 0; k < 2; ++k) dst[m][k] = *(const PG8_LAS bf16x8*)(lds + PG8_SA(b, h) + aoff + m * 2048 + k * 1024); } while (0)
; #define PG8_MMA(ai, bj, At, Bt) do { __builtin_amdgcn_s_setprio(1); _Pragma("unroll") for (int m = 0; m < 4; ++m) _Pragma("unroll") for (int n = 0; n < 2; ++n) _Pragma("unroll") for (int k = 0; k < 2; ++k) \
;         acc[ai][bj][m][n] = __builtin_amdgcn_mfma_f32_16x16x32_bf16(Bt[n][k], At[m][k], acc[ai][bj][m][n], 0, 0, 0); __builtin_amdgcn_s_setprio(0); } while (0)
; #define PG8_WAIT_V(n) asm volatile("s_waitcnt vmcnt(" #n ")" ::: "memory")
; #define PG8_WAIT_L(n) asm volatile("s_waitcnt lgkmcnt(" #n ")" ::: "memory")
; #define PG8_BAR __builtin_amdgcn_s_barrier()
; #define PG8_SCHED __builtin_amdgcn_sched_barrier(0)
; template <class Epi, class Sched, bool ALIGN_EPI = false, bool SP2 = false>
; __device__ __forceinline__ void gemm_phase(PG8_LAS unsigned char* lds, const Gemm g, const Sched& S, const Epi& E) {
;     ...
;             PG8_LDA(At, 1, 1); PG8_STAGE(PG8_SB(1, 0), b3, voffB); PG8_STAGE(PG8_SB(1, 1), b3 + hstepB, voffB); PG8_STAGE(PG8_SA(1, 0), a3, voffA);
;             PG8_WAIT_V(8); PG8_WAIT_L(0); PG8_BAR; PG8_MMA(1, 0, At, B0); PG8_MMA(1, 1, At, B1); PG8_BAR; PG8_SCHED;
	s_add_i32 s9, s9, s0
	s_mov_b32 m0, s9
	ds_read_b128 v[182:185], v165 offset:49152
	ds_read_b128 v[206:209], v165 offset:50176
	ds_read_b128 v[210:213], v165 offset:51200
	ds_read_b128 v[214:217], v165 offset:52224
	ds_read_b128 v[218:221], v165 offset:53248
	ds_read_b128 v[236:239], v165 offset:54272
	ds_read_b128 v[240:243], v165 offset:55296
	ds_read_b128 v[244:247], v165 offset:56320
	s_add_u32 s100, s80, s60
	s_addc_u32 s101, s81, s61
	global_load_lds_dwordx4 v132, s[100:101]
	s_add_i32 m0, s9, 0x2000
	s_add_u32 s10, s80, 0x20080
	s_addc_u32 s11, s81, 0
	s_add_i32 s9, s12, s0
	global_load_lds_dwordx4 v136, s[100:101]
	s_mov_b32 m0, s9
	s_nop 0
	global_load_lds_dwordx4 v132, s[10:11]
	s_add_i32 m0, s9, 0x2000
	s_nop 0
	global_load_lds_dwordx4 v136, s[10:11]
	s_mov_b32 m0, s66
	s_add_u32 s100, s84, s60
	s_addc_u32 s101, s85, s61
	global_load_lds_dwordx4 v130, s[100:101]
	s_mov_b32 m0, s67
	s_nop 0
	global_load_lds_dwordx4 v134, s[100:101]
	s_waitcnt vmcnt(8)
	s_waitcnt lgkmcnt(0)
	s_barrier
	v_mfma_f32_16x16x32_bf16 v[62:65], v[148:151], v[182:185], v[62:65]
	v_mfma_f32_16x16x32_bf16 v[58:61], v[156:159], v[182:185], v[58:61]
	v_mfma_f32_16x16x32_bf16 v[54:57], v[148:151], v[210:213], v[54:57]
	v_mfma_f32_16x16x32_bf16 v[50:53], v[156:159], v[210:213], v[50:53]
	v_mfma_f32_16x16x32_bf16 v[46:49], v[148:151], v[218:221], v[46:49]
	v_mfma_f32_16x16x32_bf16 v[42:45], v[156:159], v[218:221], v[42:45]
	v_mfma_f32_16x16x32_bf16 v[38:41], v[148:151], v[240:243], v[38:41]
	v_mfma_f32_16x16x32_bf16 v[34:37], v[156:159], v[240:243], v[34:37]
	v_mfma_f32_16x16x32_bf16 v[62:65], v[152:155], v[206:209], v[62:65]
	v_mfma_f32_16x16x32_bf16 v[58:61], v[160:163], v[206:209], v[58:61]
	v_mfma_f32_16x16x32_bf16 v[54:57], v[152:155], v[214:217], v[54:57]
	v_mfma_f32_16x16x32_bf16 v[50:53], v[160:163], v[214:217], v[50:53]
	v_mfma_f32_16x16x32_bf16 v[46:49], v[152:155], v[236:239], v[46:49]
	v_mfma_f32_16x16x32_bf16 v[42:45], v[160:163], v[236:239], v[42:45]
	v_mfma_f32_16x16x32_bf16 v[38:41], v[152:155], v[244:247], v[38:41]
	v_mfma_f32_16x16x32_bf16 v[34:37], v[160:163], v[244:247], v[34:37]
	v_mfma_f32_16x16x32_bf16 v[30:33], v[166:169], v[182:185], v[30:33]
	v_mfma_f32_16x16x32_bf16 v[26:29], v[174:177], v[182:185], v[26:29]
	v_mfma_f32_16x16x32_bf16 v[22:25], v[166:169], v[210:213], v[22:25]
	v_mfma_f32_16x16x32_bf16 v[18:21], v[174:177], v[210:213], v[18:21]
	v_mfma_f32_16x16x32_bf16 v[14:17], v[166:169], v[218:221], v[14:17]
	v_mfma_f32_16x16x32_bf16 v[10:13], v[174:177], v[218:221], v[10:13]
	v_mfma_f32_16x16x32_bf16 v[6:9], v[166:169], v[240:243], v[6:9]
	v_mfma_f32_16x16x32_bf16 v[2:5], v[174:177], v[240:243], v[2:5]
	v_mfma_f32_16x16x32_bf16 v[30:33], v[170:173], v[206:209], v[30:33]
	v_mfma_f32_16x16x32_bf16 v[26:29], v[178:181], v[206:209], v[26:29]
	v_mfma_f32_16x16x32_bf16 v[22:25], v[170:173], v[214:217], v[22:25]
	v_mfma_f32_16x16x32_bf16 v[18:21], v[178:181], v[214:217], v[18:21]
	v_mfma_f32_16x16x32_bf16 v[14:17], v[170:173], v[236:239], v[14:17]
	v_mfma_f32_16x16x32_bf16 v[10:13], v[178:181], v[236:239], v[10:13]
	v_mfma_f32_16x16x32_bf16 v[6:9], v[170:173], v[244:247], v[6:9]
	v_mfma_f32_16x16x32_bf16 v[2:5], v[178:181], v[244:247], v[2:5]
	s_barrier
	s_add_i32 s8, s8, 2
	s_add_u32 s46, s46, 0x100
	s_addc_u32 s47, s47, 0
	s_cmp_gt_u32 s8, 29
	s_cbranch_scc0 .LBB0_170
	s_and_b64 vcc, exec, s[54:55]
	s_cbranch_vccz .LBB0_173
	s_barrier

; #define PG8_STAGE(bufoff, gbase, voff) do { _Pragma("unroll") for (int _i = 0; _i < 2; ++_i) \
;         __builtin_amdgcn_global_load_lds((const unsigned*)((const char*)(gbase) + (voff)[_i]), (PG8_LAS unsigned*)(lds + (bufoff) + ldsw + _i * 8192), 16, 0, 0); } while (0)
; #define PG8_LDA(dst, b, h) do { _Pragma("unroll") for (int m = 0; m < 4; ++m) _Pragma("unroll") for (int k = 0; k < 2; ++k) dst[m][k] = *(const PG8_LAS bf16x8*)(lds + PG8_SA(b, h) + aoff + m * 2048 + k * 1024); } while (0)
; #define PG8_LDB(dst, b, h) do { _Pragma("unroll") for (int n = 0; n < 2; ++n) _Pragma("unroll") for (int k = 0; k < 2; ++k) dst[n][k] = *(const PG8_LAS bf16x8*)(lds + PG8_SB(b, h) + boff + n * 2048 + k * 1024); } while (0)
; #define PG8_WAIT_V(n) asm volatile("s_waitcnt vmcnt(" #n ")" ::: "memory")
; #define PG8_WAIT_L(n) asm volatile("s_waitcnt lgkmcnt(" #n ")" ::: "memory")
; #define PG8_BAR __builtin_amdgcn_s_barrier()
; #define PG8_SCHED __builtin_amdgcn_sched_barrier(0)
; template <class Epi, class Sched, bool ALIGN_EPI = false, bool SP2 = false>
; __device__ __forceinline__ void gemm_phase(PG8_LAS unsigned char* lds, const Gemm g, const Sched& S, const Epi& E) {
;     ...
;         const bool has_next = S.next(ui + 1, nxt);
;         const char* nA = has_next ? (const char*)g.A + (size_t)nxt.pm * tstep : cA; const char* nB = has_next ? (const char*)g.Bt + (size_t)nxt.pn * tstep : cB;
;         for (int t = 0; t < nt; t += 2) {
;             const bool last = (t == nt - 2);
;             const char* a1 = cA + (size_t)(t + 1) * kstep;
;             const char* a2 = last ? nA : cA + (size_t)(t + 2) * kstep; const char* b2 = last ? nB : cB + (size_t)(t + 2) * kstep;
;             const char* a3 = a2 + kstep; const char* b3 = b2 + kstep;
;             if (last && has_next) S.a_ready(nxt);
;             if constexpr (SP2) {
;             PG8_LDB(B0, 0, 0); PG8_LDB(B1, 0, 1); PG8_SCHED; PG8_LDA(At, 0, 0); PG8_STAGE(PG8_SA(1, 1), a1 + hstep, voffA);
;             PG8_WAIT_V(8); PG8_WAIT_L(0); PG8_BAR; PG8_MMA(0, 0, At, B0); PG8_MMA(0, 1, At, B1); PG8_BAR; PG8_SCHED;
;     ...
; #pragma unroll
;         for (int a = 0; a < 2; ++a)
; #pragma unroll
;             for (int b = 0; b < 2; ++b)
; #pragma unroll
;                 for (int m = 0; m < 4; ++m)
; #pragma unroll
;                     for (int n = 0; n < 2; ++n) acc[a][b][m][n] = (f32x4){0.f, 0.f, 0.f, 0.f};
.LBB0_787:
	s_ashr_i32 s63, s62, 31
	s_lshl_b64 s[4:5], s[62:63], 18
	v_readlane_b32 s6, v249, 4
	v_readlane_b32 s7, v249, 5
	s_add_u32 s70, s6, s4
	s_addc_u32 s71, s7, s5
	s_and_b64 s[4:5], s[78:79], exec
	s_cselect_b32 s36, s71, s69
	s_cselect_b32 s37, s70, s68
	s_ashr_i32 s55, s54, 31
	s_lshl_b64 s[4:5], s[54:55], 18
	v_readlane_b32 s6, v249, 7
	v_readlane_b32 s7, v249, 8
	s_add_u32 s84, s6, s4
	s_addc_u32 s85, s7, s5
	s_and_b64 s[4:5], s[78:79], exec
	s_cselect_b32 s4, s85, s73
	s_cselect_b32 s5, s84, s72
	s_add_u32 s68, s68, 0x20080
	s_addc_u32 s69, s69, 0
	s_add_u32 s6, s72, 0x100
	v_mov_b32_e32 v2, 0
	s_addc_u32 s7, s73, 0
	s_mov_b32 s8, -2
	v_mov_b32_e32 v3, v2
	v_mov_b32_e32 v4, v2
	v_mov_b32_e32 v5, v2
	v_mov_b32_e32 v6, v2
	v_mov_b32_e32 v7, v2
	v_mov_b32_e32 v8, v2
	v_mov_b32_e32 v9, v2
	v_mov_b32_e32 v18, v2
	v_mov_b32_e32 v19, v2
	v_mov_b32_e32 v20, v2
	v_mov_b32_e32 v21, v2
	v_mov_b32_e32 v22, v2
	v_mov_b32_e32 v23, v2
	v_mov_b32_e32 v24, v2
	v_mov_b32_e32 v25, v2
	v_mov_b32_e32 v42, v2
	v_mov_b32_e32 v43, v2
	v_mov_b32_e32 v44, v2
	v_mov_b32_e32 v45, v2
	v_mov_b32_e32 v46, v2
	v_mov_b32_e32 v47, v2
	v_mov_b32_e32 v48, v2
	v_mov_b32_e32 v49, v2
	v_mov_b32_e32 v66, v2
	v_mov_b32_e32 v67, v2
	v_mov_b32_e32 v68, v2
	v_mov_b32_e32 v69, v2
	v_mov_b32_e32 v70, v2
	v_mov_b32_e32 v71, v2
	v_mov_b32_e32 v72, v2
	v_mov_b32_e32 v73, v2
	v_mov_b32_e32 v10, v2
	v_mov_b32_e32 v11, v2
	v_mov_b32_e32 v12, v2
	v_mov_b32_e32 v13, v2
	v_mov_b32_e32 v14, v2
	v_mov_b32_e32 v15, v2
	v_mov_b32_e32 v16, v2
	v_mov_b32_e32 v17, v2
	v_mov_b32_e32 v26, v2
	v_mov_b32_e32 v27, v2
	v_mov_b32_e32 v28, v2
	v_mov_b32_e32 v29, v2
	v_mov_b32_e32 v30, v2
	v_mov_b32_e32 v31, v2
	v_mov_b32_e32 v32, v2
	v_mov_b32_e32 v33, v2
	v_mov_b32_e32 v58, v2
	v_mov_b32_e32 v59, v2
	v_mov_b32_e32 v60, v2
	v_mov_b32_e32 v61, v2
	v_mov_b32_e32 v62, v2
	v_mov_b32_e32 v63, v2
	v_mov_b32_e32 v64, v2
	v_mov_b32_e32 v65, v2
	v_mov_b32_e32 v74, v2
	v_mov_b32_e32 v75, v2
	v_mov_b32_e32 v76, v2
	v_mov_b32_e32 v77, v2
	v_mov_b32_e32 v78, v2
	v_mov_b32_e32 v79, v2
	v_mov_b32_e32 v80, v2
	v_mov_b32_e32 v81, v2
	v_mov_b32_e32 v82, v2
	v_mov_b32_e32 v83, v2
	v_mov_b32_e32 v84, v2
	v_mov_b32_e32 v85, v2
	v_mov_b32_e32 v86, v2
	v_mov_b32_e32 v87, v2
	v_mov_b32_e32 v88, v2
	v_mov_b32_e32 v89, v2
	v_mov_b32_e32 v98, v2
	v_mov_b32_e32 v99, v2
	v_mov_b32_e32 v100, v2
	v_mov_b32_e32 v101, v2
	v_mov_b32_e32 v102, v2
	v_mov_b32_e32 v103, v2
	v_mov_b32_e32 v104, v2
	v_mov_b32_e32 v105, v2
	v_mov_b32_e32 v118, v2
	v_mov_b32_e32 v119, v2
	v_mov_b32_e32 v120, v2
	v_mov_b32_e32 v121, v2
	v_mov_b32_e32 v122, v2
	v_mov_b32_e32 v123, v2
	v_mov_b32_e32 v124, v2
	v_mov_b32_e32 v125, v2
	v_mov_b32_e32 v142, v2
	v_mov_b32_e32 v143, v2
	v_mov_b32_e32 v144, v2
	v_mov_b32_e32 v145, v2
	v_mov_b32_e32 v146, v2
	v_mov_b32_e32 v147, v2
	v_mov_b32_e32 v148, v2
	v_mov_b32_e32 v149, v2
	v_mov_b32_e32 v90, v2
	v_mov_b32_e32 v91, v2
	v_mov_b32_e32 v92, v2
	v_mov_b32_e32 v93, v2
	v_mov_b32_e32 v94, v2
	v_mov_b32_e32 v95, v2
	v_mov_b32_e32 v96, v2
	v_mov_b32_e32 v97, v2
	v_mov_b32_e32 v106, v2
	v_mov_b32_e32 v107, v2
	v_mov_b32_e32 v108, v2
	v_mov_b32_e32 v109, v2
	v_mov_b32_e32 v110, v2
	v_mov_b32_e32 v111, v2
	v_mov_b32_e32 v112, v2
	v_mov_b32_e32 v113, v2
	v_mov_b32_e32 v130, v2
	v_mov_b32_e32 v131, v2
	v_mov_b32_e32 v132, v2
	v_mov_b32_e32 v133, v2
	v_mov_b32_e32 v134, v2
	v_mov_b32_e32 v135, v2
	v_mov_b32_e32 v136, v2
	v_mov_b32_e32 v137, v2
	v_mov_b32_e32 v162, v2
	v_mov_b32_e32 v163, v2
	v_mov_b32_e32 v164, v2
	v_mov_b32_e32 v165, v2
	v_mov_b32_e32 v166, v2
	v_mov_b32_e32 v167, v2
	v_mov_b32_e32 v168, v2
	v_mov_b32_e32 v169, v2
	v_add_u32_e32 v186, 0x10000, v193
	v_add_u32_e32 v187, 0x14000, v193
	v_add_u32_e32 v198, 0x18000, v193
	v_add_u32_e32 v199, 0x1c000, v193
.LBB0_788:
	s_add_u32 s9, s68, 0xfffe0080
	s_addc_u32 s10, s69, -1
	s_add_i32 s11, 0, 0x10000
	s_cmp_eq_u32 s8, 4
	s_cselect_b32 s77, s36, s10
	s_cselect_b32 s76, s37, s9
	s_cselect_b32 s73, s4, s7
	s_cselect_b32 s72, s5, s6
	s_add_i32 s9, 0, 0x14000
	ds_read_b128 v[34:37], v186
	ds_read_b128 v[38:41], v186 offset:1024
	ds_read_b128 v[50:53], v186 offset:2048
	ds_read_b128 v[54:57], v186 offset:3072
	ds_read_b128 v[114:117], v187
	ds_read_b128 v[126:129], v187 offset:1024
	ds_read_b128 v[138:141], v187 offset:2048
	ds_read_b128 v[150:153], v187 offset:3072
	s_add_i32 m0, s66, 0xc000
	ds_read_b128 v[154:157], v217
	ds_read_b128 v[158:161], v217 offset:1024
	ds_read_b128 v[170:173], v217 offset:2048
	ds_read_b128 v[206:209], v217 offset:3072
	ds_read_b128 v[210:213], v217 offset:4096
	ds_read_b128 v[218:221], v217 offset:5120
	ds_read_b128 v[236:239], v217 offset:6144
	ds_read_b128 v[240:243], v217 offset:7168
	global_load_lds_dwordx4 v180, s[68:69]
	s_add_i32 m0, s66, 0xe000
	s_nop 0
	global_load_lds_dwordx4 v182, s[68:69]
	s_waitcnt vmcnt(8)
	s_waitcnt lgkmcnt(0)
	s_barrier
; #define PG8_STAGE(bufoff, gbase, voff) do { _Pragma("unroll") for (int _i = 0; _i < 2; ++_i) \
;         __builtin_amdgcn_global_load_lds((const unsigned*)((const char*)(gbase) + (voff)[_i]), (PG8_LAS unsigned*)(lds + (bufoff) + ldsw + _i * 8192), 16, 0, 0); } while (0)
; #define PG8_LDA(dst, b, h) do { _Pragma("unroll") for (int m = 0; m < 4; ++m) _Pragma("unroll") for (int k = 0; k < 2; ++k) dst[m][k] = *(const PG8_LAS bf16x8*)(lds + PG8_SA(b, h) + aoff + m * 2048 + k * 1024); } while (0)
; #define PG8_MMA(ai, bj, At, Bt) do { __builtin_amdgcn_s_setprio(1); _Pragma("unroll") for (int m = 0; m < 4; ++m) _Pragma("unroll") for (int n = 0; n < 2; ++n) _Pragma("unroll") for (int k = 0; k < 2; ++k) \
;         acc[ai][bj][m][n] = __builtin_amdgcn_mfma_f32_16x16x32_bf16(Bt[n][k], At[m][k], acc[ai][bj][m][n], 0, 0, 0); __builtin_amdgcn_s_setprio(0); } while (0)
; #define PG8_WAIT_V(n) asm volatile("s_waitcnt vmcnt(" #n ")" ::: "memory")
; #define PG8_WAIT_L(n) asm volatile("s_waitcnt lgkmcnt(" #n ")" ::: "memory")
; #define PG8_BAR __builtin_amdgcn_s_barrier()
; #define PG8_SCHED __builtin_amdgcn_sched_barrier(0)
; template <class Epi, class Sched, bool ALIGN_EPI = false, bool SP2 = false>
; __device__ __forceinline__ void gemm_phase(PG8_LAS unsigned char* lds, const Gemm g, const Sched& S, const Epi& E) {
;     ...
;             PG8_WAIT_V(8); PG8_WAIT_L(0); PG8_BAR; PG8_MMA(0, 0, At, B0); PG8_MMA(0, 1, At, B1); PG8_BAR; PG8_SCHED;
;             PG8_LDA(At, 0, 1); PG8_STAGE(PG8_SB(0, 0), b2, voffB); PG8_STAGE(PG8_SB(0, 1), b2 + hstepB, voffB); PG8_STAGE(PG8_SA(0, 0), a2, voffA);
;             PG8_WAIT_V(8); PG8_WAIT_L(0); PG8_BAR; PG8_MMA(1, 0, At, B0); PG8_MMA(1, 1, At, B1); PG8_BAR; PG8_SCHED;
	v_mfma_f32_16x16x32_bf16 v[166:169], v[34:37], v[154:157], v[166:169]
	v_mfma_f32_16x16x32_bf16 v[162:165], v[50:53], v[154:157], v[162:165]
	v_mfma_f32_16x16x32_bf16 v[134:137], v[34:37], v[170:173], v[134:137]
	v_mfma_f32_16x16x32_bf16 v[130:133], v[50:53], v[170:173], v[130:133]
	v_mfma_f32_16x16x32_bf16 v[110:113], v[34:37], v[210:213], v[110:113]
	v_mfma_f32_16x16x32_bf16 v[106:109], v[50:53], v[210:213], v[106:109]
	v_mfma_f32_16x16x32_bf16 v[94:97], v[34:37], v[236:239], v[94:97]
	v_mfma_f32_16x16x32_bf16 v[90:93], v[50:53], v[236:239], v[90:93]
	v_mfma_f32_16x16x32_bf16 v[166:169], v[38:41], v[158:161], v[166:169]
	v_mfma_f32_16x16x32_bf16 v[162:165], v[54:57], v[158:161], v[162:165]
	v_mfma_f32_16x16x32_bf16 v[134:137], v[38:41], v[206:209], v[134:137]
	v_mfma_f32_16x16x32_bf16 v[130:133], v[54:57], v[206:209], v[130:133]
	v_mfma_f32_16x16x32_bf16 v[110:113], v[38:41], v[218:221], v[110:113]
	v_mfma_f32_16x16x32_bf16 v[106:109], v[54:57], v[218:221], v[106:109]
	v_mfma_f32_16x16x32_bf16 v[94:97], v[38:41], v[240:243], v[94:97]
	v_mfma_f32_16x16x32_bf16 v[90:93], v[54:57], v[240:243], v[90:93]
	v_mfma_f32_16x16x32_bf16 v[146:149], v[114:117], v[154:157], v[146:149]
	v_mfma_f32_16x16x32_bf16 v[142:145], v[138:141], v[154:157], v[142:145]
	v_mfma_f32_16x16x32_bf16 v[122:125], v[114:117], v[170:173], v[122:125]
	v_mfma_f32_16x16x32_bf16 v[118:121], v[138:141], v[170:173], v[118:121]
	v_mfma_f32_16x16x32_bf16 v[102:105], v[114:117], v[210:213], v[102:105]
	v_mfma_f32_16x16x32_bf16 v[98:101], v[138:141], v[210:213], v[98:101]
	v_mfma_f32_16x16x32_bf16 v[86:89], v[114:117], v[236:239], v[86:89]
	v_mfma_f32_16x16x32_bf16 v[82:85], v[138:141], v[236:239], v[82:85]
	v_mfma_f32_16x16x32_bf16 v[146:149], v[126:129], v[158:161], v[146:149]
	v_mfma_f32_16x16x32_bf16 v[142:145], v[150:153], v[158:161], v[142:145]
	v_mfma_f32_16x16x32_bf16 v[122:125], v[126:129], v[206:209], v[122:125]
	v_mfma_f32_16x16x32_bf16 v[118:121], v[150:153], v[206:209], v[118:121]
	v_mfma_f32_16x16x32_bf16 v[102:105], v[126:129], v[218:221], v[102:105]
	v_mfma_f32_16x16x32_bf16 v[98:101], v[150:153], v[218:221], v[98:101]
	v_mfma_f32_16x16x32_bf16 v[86:89], v[126:129], v[240:243], v[86:89]
	v_mfma_f32_16x16x32_bf16 v[82:85], v[150:153], v[240:243], v[82:85]
	s_barrier
	s_add_i32 s10, s11, s25
	s_mov_b32 m0, s10
	ds_read_b128 v[154:157], v217 offset:16384
	ds_read_b128 v[158:161], v217 offset:17408
	ds_read_b128 v[170:173], v217 offset:18432
	ds_read_b128 v[206:209], v217 offset:19456
	ds_read_b128 v[210:213], v217 offset:20480
	ds_read_b128 v[218:221], v217 offset:21504
	ds_read_b128 v[236:239], v217 offset:22528
	ds_read_b128 v[240:243], v217 offset:23552
	global_load_lds_dwordx4 v190, s[72:73]
	s_add_i32 m0, s10, 0x2000
	s_add_u32 s10, s72, 0x8000
	s_addc_u32 s11, s73, 0
	s_add_i32 s9, s9, s25
	global_load_lds_dwordx4 v174, s[72:73]
	s_mov_b32 m0, s9
	s_nop 0
	global_load_lds_dwordx4 v190, s[10:11]
	s_add_i32 m0, s9, 0x2000
	s_nop 0
	global_load_lds_dwordx4 v174, s[10:11]
	s_mov_b32 m0, s66
	s_nop 0
	global_load_lds_dwordx4 v178, s[76:77]
	s_mov_b32 m0, s67
	s_nop 0
	global_load_lds_dwordx4 v176, s[76:77]
	s_waitcnt vmcnt(8)
	s_waitcnt lgkmcnt(0)
	s_barrier
	v_mfma_f32_16x16x32_bf16 v[78:81], v[34:37], v[154:157], v[78:81]
	v_mfma_f32_16x16x32_bf16 v[74:77], v[50:53], v[154:157], v[74:77]
	v_mfma_f32_16x16x32_bf16 v[62:65], v[34:37], v[170:173], v[62:65]
	v_mfma_f32_16x16x32_bf16 v[58:61], v[50:53], v[170:173], v[58:61]
	v_mfma_f32_16x16x32_bf16 v[30:33], v[34:37], v[210:213], v[30:33]
	v_mfma_f32_16x16x32_bf16 v[26:29], v[50:53], v[210:213], v[26:29]
	v_mfma_f32_16x16x32_bf16 v[14:17], v[34:37], v[236:239], v[14:17]
	v_mfma_f32_16x16x32_bf16 v[10:13], v[50:53], v[236:239], v[10:13]
	v_mfma_f32_16x16x32_bf16 v[78:81], v[38:41], v[158:161], v[78:81]
	v_mfma_f32_16x16x32_bf16 v[74:77], v[54:57], v[158:161], v[74:77]
	v_mfma_f32_16x16x32_bf16 v[62:65], v[38:41], v[206:209], v[62:65]
	v_mfma_f32_16x16x32_bf16 v[58:61], v[54:57], v[206:209], v[58:61]
	v_mfma_f32_16x16x32_bf16 v[30:33], v[38:41], v[218:221], v[30:33]
	v_mfma_f32_16x16x32_bf16 v[26:29], v[54:57], v[218:221], v[26:29]
	v_mfma_f32_16x16x32_bf16 v[14:17], v[38:41], v[240:243], v[14:17]
	v_mfma_f32_16x16x32_bf16 v[10:13], v[54:57], v[240:243], v[10:13]
	v_mfma_f32_16x16x32_bf16 v[46:49], v[114:117], v[170:173], v[46:49]
	v_mfma_f32_16x16x32_bf16 v[42:45], v[138:141], v[170:173], v[42:45]
	v_mfma_f32_16x16x32_bf16 v[22:25], v[114:117], v[210:213], v[22:25]
	v_mfma_f32_16x16x32_bf16 v[18:21], v[138:141], v[210:213], v[18:21]
	v_mfma_f32_16x16x32_bf16 v[6:9], v[114:117], v[236:239], v[6:9]
	v_mfma_f32_16x16x32_bf16 v[2:5], v[138:141], v[236:239], v[2:5]
	v_mfma_f32_16x16x32_bf16 v[34:37], v[114:117], v[154:157], v[70:73]
	v_mfma_f32_16x16x32_bf16 v[38:41], v[138:141], v[154:157], v[66:69]
	v_mfma_f32_16x16x32_bf16 v[46:49], v[126:129], v[206:209], v[46:49]
	v_mfma_f32_16x16x32_bf16 v[42:45], v[150:153], v[206:209], v[42:45]
	v_mfma_f32_16x16x32_bf16 v[22:25], v[126:129], v[218:221], v[22:25]
	v_mfma_f32_16x16x32_bf16 v[18:21], v[150:153], v[218:221], v[18:21]
	v_mfma_f32_16x16x32_bf16 v[6:9], v[126:129], v[240:243], v[6:9]
	v_mfma_f32_16x16x32_bf16 v[2:5], v[150:153], v[240:243], v[2:5]
	v_mfma_f32_16x16x32_bf16 v[34:37], v[126:129], v[158:161], v[34:37]
	v_mfma_f32_16x16x32_bf16 v[38:41], v[150:153], v[158:161], v[38:41]
	s_barrier
; #define PG8_STAGE(bufoff, gbase, voff) do { _Pragma("unroll") for (int _i = 0; _i < 2; ++_i) \
;         __builtin_amdgcn_global_load_lds((const unsigned*)((const char*)(gbase) + (voff)[_i]), (PG8_LAS unsigned*)(lds + (bufoff) + ldsw + _i * 8192), 16, 0, 0); } while (0)
; #define PG8_LDA(dst, b, h) do { _Pragma("unroll") for (int m = 0; m < 4; ++m) _Pragma("unroll") for (int k = 0; k < 2; ++k) dst[m][k] = *(const PG8_LAS bf16x8*)(lds + PG8_SA(b, h) + aoff + m * 2048 + k * 1024); } while (0)
; #define PG8_LDB(dst, b, h) do { _Pragma("unroll") for (int n = 0; n < 2; ++n) _Pragma("unroll") for (int k = 0; k < 2; ++k) dst[n][k] = *(const PG8_LAS bf16x8*)(lds + PG8_SB(b, h) + boff + n * 2048 + k * 1024); } while (0)
; #define PG8_MMA(ai, bj, At, Bt) do { __builtin_amdgcn_s_setprio(1); _Pragma("unroll") for (int m = 0; m < 4; ++m) _Pragma("unroll") for (int n = 0; n < 2; ++n) _Pragma("unroll") for (int k = 0; k < 2; ++k) \
;         acc[ai][bj][m][n] = __builtin_amdgcn_mfma_f32_16x16x32_bf16(Bt[n][k], At[m][k], acc[ai][bj][m][n], 0, 0, 0); __builtin_amdgcn_s_setprio(0); } while (0)
; #define PG8_WAIT_V(n) asm volatile("s_waitcnt vmcnt(" #n ")" ::: "memory")
; #define PG8_WAIT_L(n) asm volatile("s_waitcnt lgkmcnt(" #n ")" ::: "memory")
; #define PG8_BAR __builtin_amdgcn_s_barrier()
; #define PG8_SCHED __builtin_amdgcn_sched_barrier(0)
; template <class Epi, class Sched, bool ALIGN_EPI = false, bool SP2 = false>
; __device__ __forceinline__ void gemm_phase(PG8_LAS unsigned char* lds, const Gemm g, const Sched& S, const Epi& E) {
;     ...
;             PG8_LDB(B0, 1, 0); PG8_LDB(B1, 1, 1); PG8_SCHED; PG8_LDA(At, 1, 0); PG8_STAGE(PG8_SA(0, 1), a2 + hstep, voffA);
;             PG8_WAIT_V(8); PG8_WAIT_L(0); PG8_BAR; PG8_MMA(0, 0, At, B0); PG8_MMA(0, 1, At, B1); PG8_BAR; PG8_SCHED;
;             PG8_LDA(At, 1, 1); PG8_STAGE(PG8_SB(1, 0), b3, voffB); PG8_STAGE(PG8_SB(1, 1), b3 + hstepB, voffB); PG8_STAGE(PG8_SA(1, 0), a3, voffA);
;             PG8_WAIT_V(8); PG8_WAIT_L(0); PG8_BAR; PG8_MMA(1, 0, At, B0); PG8_MMA(1, 1, At, B1); PG8_BAR; PG8_SCHED;
	s_add_i32 s9, 0, 0x18000
	s_add_i32 s12, 0, 0x1c000
	ds_read_b128 v[50:53], v198
	ds_read_b128 v[54:57], v198 offset:1024
	ds_read_b128 v[66:69], v198 offset:2048
	ds_read_b128 v[70:73], v198 offset:3072
	ds_read_b128 v[114:117], v199
	ds_read_b128 v[126:129], v199 offset:1024
	ds_read_b128 v[138:141], v199 offset:2048
	ds_read_b128 v[150:153], v199 offset:3072
	s_add_u32 s10, s76, 0x20000
	s_addc_u32 s11, s77, 0
	s_mov_b32 m0, s80
	ds_read_b128 v[154:157], v217 offset:32768
	ds_read_b128 v[158:161], v217 offset:33792
	ds_read_b128 v[170:173], v217 offset:34816
	ds_read_b128 v[206:209], v217 offset:35840
	ds_read_b128 v[210:213], v217 offset:36864
	ds_read_b128 v[218:221], v217 offset:37888
	ds_read_b128 v[236:239], v217 offset:38912
	ds_read_b128 v[240:243], v217 offset:39936
	global_load_lds_dwordx4 v178, s[10:11]
	s_mov_b32 m0, s81
	s_nop 0
	global_load_lds_dwordx4 v176, s[10:11]
	s_waitcnt vmcnt(8)
	s_waitcnt lgkmcnt(0)
	s_barrier
	v_mfma_f32_16x16x32_bf16 v[166:169], v[50:53], v[154:157], v[166:169]
	v_mfma_f32_16x16x32_bf16 v[162:165], v[66:69], v[154:157], v[162:165]
	v_mfma_f32_16x16x32_bf16 v[134:137], v[50:53], v[170:173], v[134:137]
	v_mfma_f32_16x16x32_bf16 v[130:133], v[66:69], v[170:173], v[130:133]
	v_mfma_f32_16x16x32_bf16 v[110:113], v[50:53], v[210:213], v[110:113]
	v_mfma_f32_16x16x32_bf16 v[106:109], v[66:69], v[210:213], v[106:109]
	v_mfma_f32_16x16x32_bf16 v[94:97], v[50:53], v[236:239], v[94:97]
	v_mfma_f32_16x16x32_bf16 v[90:93], v[66:69], v[236:239], v[90:93]
	v_mfma_f32_16x16x32_bf16 v[166:169], v[54:57], v[158:161], v[166:169]
	v_mfma_f32_16x16x32_bf16 v[162:165], v[70:73], v[158:161], v[162:165]
	v_mfma_f32_16x16x32_bf16 v[134:137], v[54:57], v[206:209], v[134:137]
	v_mfma_f32_16x16x32_bf16 v[130:133], v[70:73], v[206:209], v[130:133]
	v_mfma_f32_16x16x32_bf16 v[110:113], v[54:57], v[218:221], v[110:113]
	v_mfma_f32_16x16x32_bf16 v[106:109], v[70:73], v[218:221], v[106:109]
	v_mfma_f32_16x16x32_bf16 v[94:97], v[54:57], v[240:243], v[94:97]
	v_mfma_f32_16x16x32_bf16 v[90:93], v[70:73], v[240:243], v[90:93]
	v_mfma_f32_16x16x32_bf16 v[146:149], v[114:117], v[154:157], v[146:149]
	v_mfma_f32_16x16x32_bf16 v[142:145], v[138:141], v[154:157], v[142:145]
	v_mfma_f32_16x16x32_bf16 v[122:125], v[114:117], v[170:173], v[122:125]
	v_mfma_f32_16x16x32_bf16 v[118:121], v[138:141], v[170:173], v[118:121]
	v_mfma_f32_16x16x32_bf16 v[102:105], v[114:117], v[210:213], v[102:105]
	v_mfma_f32_16x16x32_bf16 v[98:101], v[138:141], v[210:213], v[98:101]
	v_mfma_f32_16x16x32_bf16 v[86:89], v[114:117], v[236:239], v[86:89]
	v_mfma_f32_16x16x32_bf16 v[82:85], v[138:141], v[236:239], v[82:85]
	v_mfma_f32_16x16x32_bf16 v[146:149], v[126:129], v[158:161], v[146:149]
	v_mfma_f32_16x16x32_bf16 v[142:145], v[150:153], v[158:161], v[142:145]
	v_mfma_f32_16x16x32_bf16 v[122:125], v[126:129], v[206:209], v[122:125]
	v_mfma_f32_16x16x32_bf16 v[118:121], v[150:153], v[206:209], v[118:121]
	v_mfma_f32_16x16x32_bf16 v[102:105], v[126:129], v[218:221], v[102:105]
	v_mfma_f32_16x16x32_bf16 v[98:101], v[150:153], v[218:221], v[98:101]
	v_mfma_f32_16x16x32_bf16 v[86:89], v[126:129], v[240:243], v[86:89]
	v_mfma_f32_16x16x32_bf16 v[82:85], v[150:153], v[240:243], v[82:85]
	s_barrier
	s_add_i32 s9, s9, s25
	s_mov_b32 m0, s9
	ds_read_b128 v[154:157], v217 offset:49152
	ds_read_b128 v[158:161], v217 offset:50176
	ds_read_b128 v[170:173], v217 offset:51200
	ds_read_b128 v[206:209], v217 offset:52224
	ds_read_b128 v[210:213], v217 offset:53248
	ds_read_b128 v[218:221], v217 offset:54272
	ds_read_b128 v[236:239], v217 offset:55296
	ds_read_b128 v[240:243], v217 offset:56320
	s_add_u32 s100, s72, s60
	s_addc_u32 s101, s73, s61
	global_load_lds_dwordx4 v190, s[100:101]
	s_add_i32 m0, s9, 0x2000
	s_add_u32 s10, s72, 0x8080
	s_addc_u32 s11, s73, 0
	s_add_i32 s9, s12, s25
	global_load_lds_dwordx4 v174, s[100:101]
	s_mov_b32 m0, s9
	s_nop 0
	global_load_lds_dwordx4 v190, s[10:11]
	s_add_i32 m0, s9, 0x2000
	s_nop 0
	global_load_lds_dwordx4 v174, s[10:11]
	s_mov_b32 m0, s82
	s_add_u32 s100, s76, s60
	s_addc_u32 s101, s77, s61
	global_load_lds_dwordx4 v178, s[100:101]
	s_mov_b32 m0, s92
	s_nop 0
	global_load_lds_dwordx4 v176, s[100:101]
	s_waitcnt vmcnt(8)
	s_waitcnt lgkmcnt(0)
	s_barrier
	v_mfma_f32_16x16x32_bf16 v[78:81], v[50:53], v[154:157], v[78:81]
	v_mfma_f32_16x16x32_bf16 v[74:77], v[66:69], v[154:157], v[74:77]
	v_mfma_f32_16x16x32_bf16 v[62:65], v[50:53], v[170:173], v[62:65]
	v_mfma_f32_16x16x32_bf16 v[58:61], v[66:69], v[170:173], v[58:61]
	v_mfma_f32_16x16x32_bf16 v[30:33], v[50:53], v[210:213], v[30:33]
	v_mfma_f32_16x16x32_bf16 v[26:29], v[66:69], v[210:213], v[26:29]
	v_mfma_f32_16x16x32_bf16 v[14:17], v[50:53], v[236:239], v[14:17]
	v_mfma_f32_16x16x32_bf16 v[10:13], v[66:69], v[236:239], v[10:13]
	v_mfma_f32_16x16x32_bf16 v[78:81], v[54:57], v[158:161], v[78:81]
	v_mfma_f32_16x16x32_bf16 v[74:77], v[70:73], v[158:161], v[74:77]
	v_mfma_f32_16x16x32_bf16 v[62:65], v[54:57], v[206:209], v[62:65]
	v_mfma_f32_16x16x32_bf16 v[58:61], v[70:73], v[206:209], v[58:61]
	v_mfma_f32_16x16x32_bf16 v[30:33], v[54:57], v[218:221], v[30:33]
	v_mfma_f32_16x16x32_bf16 v[26:29], v[70:73], v[218:221], v[26:29]
	v_mfma_f32_16x16x32_bf16 v[14:17], v[54:57], v[240:243], v[14:17]
	v_mfma_f32_16x16x32_bf16 v[10:13], v[70:73], v[240:243], v[10:13]
	v_mfma_f32_16x16x32_bf16 v[34:37], v[114:117], v[154:157], v[34:37]
	v_mfma_f32_16x16x32_bf16 v[70:73], v[126:129], v[158:161], v[34:37]
	v_mfma_f32_16x16x32_bf16 v[34:37], v[138:141], v[154:157], v[38:41]
	v_mfma_f32_16x16x32_bf16 v[66:69], v[150:153], v[158:161], v[34:37]
	v_mfma_f32_16x16x32_bf16 v[34:37], v[114:117], v[170:173], v[46:49]
	v_mfma_f32_16x16x32_bf16 v[46:49], v[126:129], v[206:209], v[34:37]
	v_mfma_f32_16x16x32_bf16 v[34:37], v[138:141], v[170:173], v[42:45]
	v_mfma_f32_16x16x32_bf16 v[22:25], v[114:117], v[210:213], v[22:25]
	v_mfma_f32_16x16x32_bf16 v[18:21], v[138:141], v[210:213], v[18:21]
	v_mfma_f32_16x16x32_bf16 v[6:9], v[114:117], v[236:239], v[6:9]
	v_mfma_f32_16x16x32_bf16 v[2:5], v[138:141], v[236:239], v[2:5]
	v_mfma_f32_16x16x32_bf16 v[42:45], v[150:153], v[206:209], v[34:37]
	v_mfma_f32_16x16x32_bf16 v[22:25], v[126:129], v[218:221], v[22:25]
	v_mfma_f32_16x16x32_bf16 v[18:21], v[150:153], v[218:221], v[18:21]
	v_mfma_f32_16x16x32_bf16 v[6:9], v[126:129], v[240:243], v[6:9]
	v_mfma_f32_16x16x32_bf16 v[2:5], v[150:153], v[240:243], v[2:5]
	s_barrier
	s_add_i32 s8, s8, 2
	s_add_u32 s68, s68, 0x100
	s_addc_u32 s69, s69, 0
	s_add_u32 s6, s6, 0x100
	s_addc_u32 s7, s7, 0
	s_cmp_gt_u32 s8, 5
	s_cbranch_scc0 .LBB0_788
	s_and_b64 vcc, exec, s[46:47]
	s_cbranch_vccz .LBB0_791
	s_barrier

; #define PG8_STAGE(bufoff, gbase, voff) do { _Pragma("unroll") for (int _i = 0; _i < 2; ++_i) \
;         __builtin_amdgcn_global_load_lds((const unsigned*)((const char*)(gbase) + (voff)[_i]), (PG8_LAS unsigned*)(lds + (bufoff) + ldsw + _i * 8192), 16, 0, 0); } while (0)
; #define PG8_LDA(dst, b, h) do { _Pragma("unroll") for (int m = 0; m < 4; ++m) _Pragma("unroll") for (int k = 0; k < 2; ++k) dst[m][k] = *(const PG8_LAS bf16x8*)(lds + PG8_SA(b, h) + aoff + m * 2048 + k * 1024); } while (0)
; #define PG8_LDB(dst, b, h) do { _Pragma("unroll") for (int n = 0; n < 2; ++n) _Pragma("unroll") for (int k = 0; k < 2; ++k) dst[n][k] = *(const PG8_LAS bf16x8*)(lds + PG8_SB(b, h) + boff + n * 2048 + k * 1024); } while (0)
; #define PG8_WAIT_V(n) asm volatile("s_waitcnt vmcnt(" #n ")" ::: "memory")
; #define PG8_WAIT_L(n) asm volatile("s_waitcnt lgkmcnt(" #n ")" ::: "memory")
; #define PG8_BAR __builtin_amdgcn_s_barrier()
; #define PG8_SCHED __builtin_amdgcn_sched_barrier(0)
; template <class Epi, class Sched, bool ALIGN_EPI = false, bool SP2 = false>
; __device__ __forceinline__ void gemm_phase(PG8_LAS unsigned char* lds, const Gemm g, const Sched& S, const Epi& E) {
;     ...
;         const bool has_next = S.next(ui + 1, nxt);
;         const char* nA = has_next ? (const char*)g.A + (size_t)nxt.pm * tstep : cA; const char* nB = has_next ? (const char*)g.Bt + (size_t)nxt.pn * tstep : cB;
;         for (int t = 0; t < nt; t += 2) {
;             const bool last = (t == nt - 2);
;             const char* a1 = cA + (size_t)(t + 1) * kstep;
;             const char* a2 = last ? nA : cA + (size_t)(t + 2) * kstep; const char* b2 = last ? nB : cB + (size_t)(t + 2) * kstep;
;             const char* a3 = a2 + kstep; const char* b3 = b2 + kstep;
;             if (last && has_next) S.a_ready(nxt);
;             if constexpr (SP2) {
;             PG8_LDB(B0, 0, 0); PG8_LDB(B1, 0, 1); PG8_SCHED; PG8_LDA(At, 0, 0); PG8_STAGE(PG8_SA(1, 1), a1 + hstep, voffA);
;             PG8_WAIT_V(8); PG8_WAIT_L(0); PG8_BAR; PG8_MMA(0, 0, At, B0); PG8_MMA(0, 1, At, B1); PG8_BAR; PG8_SCHED;
;     ...
; #pragma unroll
;         for (int a = 0; a < 2; ++a)
; #pragma unroll
;             for (int b = 0; b < 2; ++b)
; #pragma unroll
;                 for (int m = 0; m < 4; ++m)
; #pragma unroll
;                     for (int n = 0; n < 2; ++n) acc[a][b][m][n] = (f32x4){0.f, 0.f, 0.f, 0.f};
.LBB0_926:
	s_ashr_i32 s73, s72, 31
	s_lshl_b64 s[4:5], s[72:73], 20
	v_readlane_b32 s6, v249, 9
	v_readlane_b32 s7, v249, 10
	s_add_u32 s76, s6, s4
	s_addc_u32 s77, s7, s5
	s_and_b64 s[4:5], s[92:93], exec
	s_cselect_b32 s36, s77, s39
	s_cselect_b32 s37, s76, s38
	s_ashr_i32 s69, s68, 31
	s_lshl_b64 s[4:5], s[68:69], 20
	v_readlane_b32 s6, v249, 17
	v_readlane_b32 s7, v249, 18
	s_add_u32 s80, s6, s4
	s_addc_u32 s81, s7, s5
	s_and_b64 s[4:5], s[92:93], exec
	s_cselect_b32 s4, s81, s47
	s_cselect_b32 s5, s80, s46
	s_add_u32 s38, s38, 0x80080
	s_addc_u32 s39, s39, 0
	s_add_u32 s6, s46, 0x100
	v_mov_b32_e32 v2, 0
	s_addc_u32 s7, s47, 0
	s_mov_b32 s8, -2
	v_mov_b32_e32 v3, v2
	v_mov_b32_e32 v4, v2
	v_mov_b32_e32 v5, v2
	v_mov_b32_e32 v6, v2
	v_mov_b32_e32 v7, v2
	v_mov_b32_e32 v8, v2
	v_mov_b32_e32 v9, v2
	v_mov_b32_e32 v18, v2
	v_mov_b32_e32 v19, v2
	v_mov_b32_e32 v20, v2
	v_mov_b32_e32 v21, v2
	v_mov_b32_e32 v22, v2
	v_mov_b32_e32 v23, v2
	v_mov_b32_e32 v24, v2
	v_mov_b32_e32 v25, v2
	v_mov_b32_e32 v34, v2
	s_waitcnt lgkmcnt(0)
	v_mov_b32_e32 v35, v2
	v_mov_b32_e32 v36, v2
	v_mov_b32_e32 v37, v2
	v_mov_b32_e32 v38, v2
	v_mov_b32_e32 v39, v2
	v_mov_b32_e32 v40, v2
	v_mov_b32_e32 v41, v2
	v_mov_b32_e32 v50, v2
	v_mov_b32_e32 v51, v2
	v_mov_b32_e32 v52, v2
	v_mov_b32_e32 v53, v2
	v_mov_b32_e32 v54, v2
	v_mov_b32_e32 v55, v2
	v_mov_b32_e32 v56, v2
	v_mov_b32_e32 v57, v2
	v_mov_b32_e32 v10, v2
	v_mov_b32_e32 v11, v2
	v_mov_b32_e32 v12, v2
	v_mov_b32_e32 v13, v2
	v_mov_b32_e32 v14, v2
	v_mov_b32_e32 v15, v2
	v_mov_b32_e32 v16, v2
	v_mov_b32_e32 v17, v2
	v_mov_b32_e32 v26, v2
	v_mov_b32_e32 v27, v2
	v_mov_b32_e32 v28, v2
	v_mov_b32_e32 v29, v2
	v_mov_b32_e32 v30, v2
	v_mov_b32_e32 v31, v2
	v_mov_b32_e32 v32, v2
	v_mov_b32_e32 v33, v2
	v_mov_b32_e32 v42, v2
	v_mov_b32_e32 v43, v2
	v_mov_b32_e32 v44, v2
	v_mov_b32_e32 v45, v2
	v_mov_b32_e32 v46, v2
	v_mov_b32_e32 v47, v2
	v_mov_b32_e32 v48, v2
	v_mov_b32_e32 v49, v2
	v_mov_b32_e32 v58, v2
	v_mov_b32_e32 v59, v2
	v_mov_b32_e32 v60, v2
	v_mov_b32_e32 v61, v2
	v_mov_b32_e32 v62, v2
	v_mov_b32_e32 v63, v2
	v_mov_b32_e32 v64, v2
	v_mov_b32_e32 v65, v2
	v_mov_b32_e32 v74, v2
	v_mov_b32_e32 v75, v2
	v_mov_b32_e32 v76, v2
	v_mov_b32_e32 v77, v2
	v_mov_b32_e32 v82, v2
	v_mov_b32_e32 v83, v2
	v_mov_b32_e32 v84, v2
	v_mov_b32_e32 v85, v2
	v_mov_b32_e32 v98, v2
	v_mov_b32_e32 v99, v2
	v_mov_b32_e32 v100, v2
	v_mov_b32_e32 v101, v2
	v_mov_b32_e32 v102, v2
	v_mov_b32_e32 v103, v2
	v_mov_b32_e32 v104, v2
	v_mov_b32_e32 v105, v2
	v_mov_b32_e32 v114, v2
	v_mov_b32_e32 v115, v2
	v_mov_b32_e32 v116, v2
	v_mov_b32_e32 v117, v2
	v_mov_b32_e32 v118, v2
	v_mov_b32_e32 v119, v2
	v_mov_b32_e32 v120, v2
	v_mov_b32_e32 v121, v2
	v_mov_b32_e32 v130, v2
	v_mov_b32_e32 v131, v2
	v_mov_b32_e32 v132, v2
	v_mov_b32_e32 v133, v2
	v_mov_b32_e32 v134, v2
	v_mov_b32_e32 v135, v2
	v_mov_b32_e32 v136, v2
	v_mov_b32_e32 v137, v2
	v_mov_b32_e32 v90, v2
	v_mov_b32_e32 v91, v2
	v_mov_b32_e32 v92, v2
	v_mov_b32_e32 v93, v2
	v_mov_b32_e32 v94, v2
	v_mov_b32_e32 v95, v2
	v_mov_b32_e32 v96, v2
	v_mov_b32_e32 v97, v2
	v_mov_b32_e32 v106, v2
	v_mov_b32_e32 v107, v2
	v_mov_b32_e32 v108, v2
	v_mov_b32_e32 v109, v2
	v_mov_b32_e32 v110, v2
	v_mov_b32_e32 v111, v2
	v_mov_b32_e32 v112, v2
	v_mov_b32_e32 v113, v2
	v_mov_b32_e32 v122, v2
	v_mov_b32_e32 v123, v2
	v_mov_b32_e32 v124, v2
	v_mov_b32_e32 v125, v2
	v_mov_b32_e32 v126, v2
	v_mov_b32_e32 v127, v2
	v_mov_b32_e32 v128, v2
	v_mov_b32_e32 v129, v2
	v_mov_b32_e32 v138, v2
	v_mov_b32_e32 v139, v2
	v_mov_b32_e32 v140, v2
	v_mov_b32_e32 v141, v2
	v_mov_b32_e32 v142, v2
	v_mov_b32_e32 v143, v2
	v_mov_b32_e32 v144, v2
	v_mov_b32_e32 v145, v2
	v_add_u32_e32 v186, 0x10000, v193
	v_add_u32_e32 v187, 0x14000, v193
	v_add_u32_e32 v198, 0x18000, v193
	v_add_u32_e32 v199, 0x1c000, v193
.LBB0_927:
	s_add_u32 s9, s38, 0xfff80080
	s_addc_u32 s10, s39, -1
	s_add_i32 s11, 0, 0x10000
	s_cmp_eq_u32 s8, 28
	s_cselect_b32 s95, s36, s10
	s_cselect_b32 s94, s37, s9
	s_cselect_b32 s47, s4, s7
	s_cselect_b32 s46, s5, s6
	s_add_i32 s9, 0, 0x14000
	ds_read_b128 v[66:69], v186
	ds_read_b128 v[70:73], v186 offset:1024
	ds_read_b128 v[78:81], v186 offset:2048
	ds_read_b128 v[86:89], v186 offset:3072
	ds_read_b128 v[146:149], v187
	ds_read_b128 v[150:153], v187 offset:1024
	ds_read_b128 v[154:157], v187 offset:2048
	ds_read_b128 v[158:161], v187 offset:3072
	s_add_i32 m0, s66, 0xc000
	ds_read_b128 v[162:165], v236
	ds_read_b128 v[166:169], v236 offset:1024
	ds_read_b128 v[170:173], v236 offset:2048
	ds_read_b128 v[174:177], v236 offset:3072
	ds_read_b128 v[178:181], v236 offset:4096
	ds_read_b128 v[182:185], v236 offset:5120
	ds_read_b128 v[216:219], v236 offset:6144
	ds_read_b128 v[220:223], v236 offset:7168
	global_load_lds_dwordx4 v212, s[38:39]
	s_add_i32 m0, s66, 0xe000
	s_nop 0
	global_load_lds_dwordx4 v214, s[38:39]
	s_waitcnt vmcnt(8)
	s_waitcnt lgkmcnt(0)
	s_barrier
; #define PG8_STAGE(bufoff, gbase, voff) do { _Pragma("unroll") for (int _i = 0; _i < 2; ++_i) \
;         __builtin_amdgcn_global_load_lds((const unsigned*)((const char*)(gbase) + (voff)[_i]), (PG8_LAS unsigned*)(lds + (bufoff) + ldsw + _i * 8192), 16, 0, 0); } while (0)
; #define PG8_LDA(dst, b, h) do { _Pragma("unroll") for (int m = 0; m < 4; ++m) _Pragma("unroll") for (int k = 0; k < 2; ++k) dst[m][k] = *(const PG8_LAS bf16x8*)(lds + PG8_SA(b, h) + aoff + m * 2048 + k * 1024); } while (0)
; #define PG8_MMA(ai, bj, At, Bt) do { __builtin_amdgcn_s_setprio(1); _Pragma("unroll") for (int m = 0; m < 4; ++m) _Pragma("unroll") for (int n = 0; n < 2; ++n) _Pragma("unroll") for (int k = 0; k < 2; ++k) \
;         acc[ai][bj][m][n] = __builtin_amdgcn_mfma_f32_16x16x32_bf16(Bt[n][k], At[m][k], acc[ai][bj][m][n], 0, 0, 0); __builtin_amdgcn_s_setprio(0); } while (0)
; #define PG8_WAIT_V(n) asm volatile("s_waitcnt vmcnt(" #n ")" ::: "memory")
; #define PG8_WAIT_L(n) asm volatile("s_waitcnt lgkmcnt(" #n ")" ::: "memory")
; #define PG8_BAR __builtin_amdgcn_s_barrier()
; #define PG8_SCHED __builtin_amdgcn_sched_barrier(0)
; template <class Epi, class Sched, bool ALIGN_EPI = false, bool SP2 = false>
; __device__ __forceinline__ void gemm_phase(PG8_LAS unsigned char* lds, const Gemm g, const Sched& S, const Epi& E) {
;     ...
;             PG8_WAIT_V(8); PG8_WAIT_L(0); PG8_BAR; PG8_MMA(0, 0, At, B0); PG8_MMA(0, 1, At, B1); PG8_BAR; PG8_SCHED;
;             PG8_LDA(At, 0, 1); PG8_STAGE(PG8_SB(0, 0), b2, voffB); PG8_STAGE(PG8_SB(0, 1), b2 + hstepB, voffB); PG8_STAGE(PG8_SA(0, 0), a2, voffA);
;             PG8_WAIT_V(8); PG8_WAIT_L(0); PG8_BAR; PG8_MMA(1, 0, At, B0); PG8_MMA(1, 1, At, B1); PG8_BAR; PG8_SCHED;
	v_mfma_f32_16x16x32_bf16 v[142:145], v[66:69], v[162:165], v[142:145]
	v_mfma_f32_16x16x32_bf16 v[138:141], v[78:81], v[162:165], v[138:141]
	v_mfma_f32_16x16x32_bf16 v[126:129], v[66:69], v[170:173], v[126:129]
	v_mfma_f32_16x16x32_bf16 v[122:125], v[78:81], v[170:173], v[122:125]
	v_mfma_f32_16x16x32_bf16 v[110:113], v[66:69], v[178:181], v[110:113]
	v_mfma_f32_16x16x32_bf16 v[106:109], v[78:81], v[178:181], v[106:109]
	v_mfma_f32_16x16x32_bf16 v[94:97], v[66:69], v[216:219], v[94:97]
	v_mfma_f32_16x16x32_bf16 v[90:93], v[78:81], v[216:219], v[90:93]
	v_mfma_f32_16x16x32_bf16 v[142:145], v[70:73], v[166:169], v[142:145]
	v_mfma_f32_16x16x32_bf16 v[138:141], v[86:89], v[166:169], v[138:141]
	v_mfma_f32_16x16x32_bf16 v[126:129], v[70:73], v[174:177], v[126:129]
	v_mfma_f32_16x16x32_bf16 v[122:125], v[86:89], v[174:177], v[122:125]
	v_mfma_f32_16x16x32_bf16 v[110:113], v[70:73], v[182:185], v[110:113]
	v_mfma_f32_16x16x32_bf16 v[106:109], v[86:89], v[182:185], v[106:109]
	v_mfma_f32_16x16x32_bf16 v[94:97], v[70:73], v[220:223], v[94:97]
	v_mfma_f32_16x16x32_bf16 v[90:93], v[86:89], v[220:223], v[90:93]
	v_mfma_f32_16x16x32_bf16 v[134:137], v[146:149], v[162:165], v[134:137]
	v_mfma_f32_16x16x32_bf16 v[130:133], v[154:157], v[162:165], v[130:133]
	v_mfma_f32_16x16x32_bf16 v[118:121], v[146:149], v[170:173], v[118:121]
	v_mfma_f32_16x16x32_bf16 v[114:117], v[154:157], v[170:173], v[114:117]
	v_mfma_f32_16x16x32_bf16 v[102:105], v[146:149], v[178:181], v[102:105]
	v_mfma_f32_16x16x32_bf16 v[98:101], v[154:157], v[178:181], v[98:101]
	v_mfma_f32_16x16x32_bf16 v[82:85], v[146:149], v[216:219], v[82:85]
	v_mfma_f32_16x16x32_bf16 v[74:77], v[154:157], v[216:219], v[74:77]
	v_mfma_f32_16x16x32_bf16 v[134:137], v[150:153], v[166:169], v[134:137]
	v_mfma_f32_16x16x32_bf16 v[130:133], v[158:161], v[166:169], v[130:133]
	v_mfma_f32_16x16x32_bf16 v[118:121], v[150:153], v[174:177], v[118:121]
	v_mfma_f32_16x16x32_bf16 v[114:117], v[158:161], v[174:177], v[114:117]
	v_mfma_f32_16x16x32_bf16 v[102:105], v[150:153], v[182:185], v[102:105]
	v_mfma_f32_16x16x32_bf16 v[98:101], v[158:161], v[182:185], v[98:101]
	v_mfma_f32_16x16x32_bf16 v[82:85], v[150:153], v[220:223], v[82:85]
	v_mfma_f32_16x16x32_bf16 v[74:77], v[158:161], v[220:223], v[74:77]
	s_barrier
	s_add_i32 s10, s11, s25
	s_mov_b32 m0, s10
	ds_read_b128 v[162:165], v236 offset:16384
	ds_read_b128 v[166:169], v236 offset:17408
	ds_read_b128 v[170:173], v236 offset:18432
	ds_read_b128 v[174:177], v236 offset:19456
	ds_read_b128 v[178:181], v236 offset:20480
	ds_read_b128 v[182:185], v236 offset:21504
	ds_read_b128 v[216:219], v236 offset:22528
	ds_read_b128 v[220:223], v236 offset:23552
	global_load_lds_dwordx4 v190, s[46:47]
	s_add_i32 m0, s10, 0x2000
	s_add_u32 s10, s46, 0x20000
	s_addc_u32 s11, s47, 0
	s_add_i32 s9, s9, s25
	global_load_lds_dwordx4 v206, s[46:47]
	s_mov_b32 m0, s9
	s_nop 0
	global_load_lds_dwordx4 v190, s[10:11]
	s_add_i32 m0, s9, 0x2000
	s_nop 0
	global_load_lds_dwordx4 v206, s[10:11]
	s_mov_b32 m0, s66
	s_nop 0
	global_load_lds_dwordx4 v210, s[94:95]
	s_mov_b32 m0, s67
	s_nop 0
	global_load_lds_dwordx4 v208, s[94:95]
	s_waitcnt vmcnt(8)
	s_waitcnt lgkmcnt(0)
	s_barrier
	v_mfma_f32_16x16x32_bf16 v[62:65], v[66:69], v[162:165], v[62:65]
	v_mfma_f32_16x16x32_bf16 v[58:61], v[78:81], v[162:165], v[58:61]
	v_mfma_f32_16x16x32_bf16 v[46:49], v[66:69], v[170:173], v[46:49]
	v_mfma_f32_16x16x32_bf16 v[42:45], v[78:81], v[170:173], v[42:45]
	v_mfma_f32_16x16x32_bf16 v[30:33], v[66:69], v[178:181], v[30:33]
	v_mfma_f32_16x16x32_bf16 v[26:29], v[78:81], v[178:181], v[26:29]
	v_mfma_f32_16x16x32_bf16 v[14:17], v[66:69], v[216:219], v[14:17]
	v_mfma_f32_16x16x32_bf16 v[10:13], v[78:81], v[216:219], v[10:13]
	v_mfma_f32_16x16x32_bf16 v[62:65], v[70:73], v[166:169], v[62:65]
	v_mfma_f32_16x16x32_bf16 v[58:61], v[86:89], v[166:169], v[58:61]
	v_mfma_f32_16x16x32_bf16 v[46:49], v[70:73], v[174:177], v[46:49]
	v_mfma_f32_16x16x32_bf16 v[42:45], v[86:89], v[174:177], v[42:45]
	v_mfma_f32_16x16x32_bf16 v[30:33], v[70:73], v[182:185], v[30:33]
	v_mfma_f32_16x16x32_bf16 v[26:29], v[86:89], v[182:185], v[26:29]
	v_mfma_f32_16x16x32_bf16 v[14:17], v[70:73], v[220:223], v[14:17]
	v_mfma_f32_16x16x32_bf16 v[10:13], v[86:89], v[220:223], v[10:13]
	v_mfma_f32_16x16x32_bf16 v[54:57], v[146:149], v[162:165], v[54:57]
	v_mfma_f32_16x16x32_bf16 v[50:53], v[154:157], v[162:165], v[50:53]
	v_mfma_f32_16x16x32_bf16 v[38:41], v[146:149], v[170:173], v[38:41]
	v_mfma_f32_16x16x32_bf16 v[34:37], v[154:157], v[170:173], v[34:37]
	v_mfma_f32_16x16x32_bf16 v[22:25], v[146:149], v[178:181], v[22:25]
	v_mfma_f32_16x16x32_bf16 v[18:21], v[154:157], v[178:181], v[18:21]
	v_mfma_f32_16x16x32_bf16 v[6:9], v[146:149], v[216:219], v[6:9]
	v_mfma_f32_16x16x32_bf16 v[2:5], v[154:157], v[216:219], v[2:5]
	v_mfma_f32_16x16x32_bf16 v[54:57], v[150:153], v[166:169], v[54:57]
	v_mfma_f32_16x16x32_bf16 v[50:53], v[158:161], v[166:169], v[50:53]
	v_mfma_f32_16x16x32_bf16 v[38:41], v[150:153], v[174:177], v[38:41]
	v_mfma_f32_16x16x32_bf16 v[34:37], v[158:161], v[174:177], v[34:37]
	v_mfma_f32_16x16x32_bf16 v[22:25], v[150:153], v[182:185], v[22:25]
	v_mfma_f32_16x16x32_bf16 v[18:21], v[158:161], v[182:185], v[18:21]
	v_mfma_f32_16x16x32_bf16 v[6:9], v[150:153], v[220:223], v[6:9]
	v_mfma_f32_16x16x32_bf16 v[2:5], v[158:161], v[220:223], v[2:5]
	s_barrier
; #define PG8_STAGE(bufoff, gbase, voff) do { _Pragma("unroll") for (int _i = 0; _i < 2; ++_i) \
;         __builtin_amdgcn_global_load_lds((const unsigned*)((const char*)(gbase) + (voff)[_i]), (PG8_LAS unsigned*)(lds + (bufoff) + ldsw + _i * 8192), 16, 0, 0); } while (0)
; #define PG8_LDA(dst, b, h) do { _Pragma("unroll") for (int m = 0; m < 4; ++m) _Pragma("unroll") for (int k = 0; k < 2; ++k) dst[m][k] = *(const PG8_LAS bf16x8*)(lds + PG8_SA(b, h) + aoff + m * 2048 + k * 1024); } while (0)
; #define PG8_LDB(dst, b, h) do { _Pragma("unroll") for (int n = 0; n < 2; ++n) _Pragma("unroll") for (int k = 0; k < 2; ++k) dst[n][k] = *(const PG8_LAS bf16x8*)(lds + PG8_SB(b, h) + boff + n * 2048 + k * 1024); } while (0)
; #define PG8_MMA(ai, bj, At, Bt) do { __builtin_amdgcn_s_setprio(1); _Pragma("unroll") for (int m = 0; m < 4; ++m) _Pragma("unroll") for (int n = 0; n < 2; ++n) _Pragma("unroll") for (int k = 0; k < 2; ++k) \
;         acc[ai][bj][m][n] = __builtin_amdgcn_mfma_f32_16x16x32_bf16(Bt[n][k], At[m][k], acc[ai][bj][m][n], 0, 0, 0); __builtin_amdgcn_s_setprio(0); } while (0)
; #define PG8_WAIT_V(n) asm volatile("s_waitcnt vmcnt(" #n ")" ::: "memory")
; #define PG8_WAIT_L(n) asm volatile("s_waitcnt lgkmcnt(" #n ")" ::: "memory")
; #define PG8_BAR __builtin_amdgcn_s_barrier()
; #define PG8_SCHED __builtin_amdgcn_sched_barrier(0)
; template <class Epi, class Sched, bool ALIGN_EPI = false, bool SP2 = false>
; __device__ __forceinline__ void gemm_phase(PG8_LAS unsigned char* lds, const Gemm g, const Sched& S, const Epi& E) {
;     ...
;             PG8_LDB(B0, 1, 0); PG8_LDB(B1, 1, 1); PG8_SCHED; PG8_LDA(At, 1, 0); PG8_STAGE(PG8_SA(0, 1), a2 + hstep, voffA);
;             PG8_WAIT_V(8); PG8_WAIT_L(0); PG8_BAR; PG8_MMA(0, 0, At, B0); PG8_MMA(0, 1, At, B1); PG8_BAR; PG8_SCHED;
;             PG8_LDA(At, 1, 1); PG8_STAGE(PG8_SB(1, 0), b3, voffB); PG8_STAGE(PG8_SB(1, 1), b3 + hstepB, voffB); PG8_STAGE(PG8_SA(1, 0), a3, voffA);
;             PG8_WAIT_V(8); PG8_WAIT_L(0); PG8_BAR; PG8_MMA(1, 0, At, B0); PG8_MMA(1, 1, At, B1); PG8_BAR; PG8_SCHED;
	s_add_i32 s9, 0, 0x18000
	s_add_i32 s12, 0, 0x1c000
	ds_read_b128 v[66:69], v198
	ds_read_b128 v[70:73], v198 offset:1024
	ds_read_b128 v[78:81], v198 offset:2048
	ds_read_b128 v[86:89], v198 offset:3072
	ds_read_b128 v[146:149], v199
	ds_read_b128 v[150:153], v199 offset:1024
	ds_read_b128 v[154:157], v199 offset:2048
	ds_read_b128 v[158:161], v199 offset:3072
	s_add_u32 s10, s94, 0x80000
	s_addc_u32 s11, s95, 0
	s_mov_b32 m0, s59
	ds_read_b128 v[162:165], v236 offset:32768
	ds_read_b128 v[166:169], v236 offset:33792
	ds_read_b128 v[170:173], v236 offset:34816
	ds_read_b128 v[174:177], v236 offset:35840
	ds_read_b128 v[178:181], v236 offset:36864
	ds_read_b128 v[182:185], v236 offset:37888
	ds_read_b128 v[216:219], v236 offset:38912
	ds_read_b128 v[220:223], v236 offset:39936
	global_load_lds_dwordx4 v210, s[10:11]
	s_mov_b32 m0, s74
	s_nop 0
	global_load_lds_dwordx4 v208, s[10:11]
	s_waitcnt vmcnt(8)
	s_waitcnt lgkmcnt(0)
	s_barrier
	v_mfma_f32_16x16x32_bf16 v[142:145], v[66:69], v[162:165], v[142:145]
	v_mfma_f32_16x16x32_bf16 v[138:141], v[78:81], v[162:165], v[138:141]
	v_mfma_f32_16x16x32_bf16 v[126:129], v[66:69], v[170:173], v[126:129]
	v_mfma_f32_16x16x32_bf16 v[122:125], v[78:81], v[170:173], v[122:125]
	v_mfma_f32_16x16x32_bf16 v[110:113], v[66:69], v[178:181], v[110:113]
	v_mfma_f32_16x16x32_bf16 v[106:109], v[78:81], v[178:181], v[106:109]
	v_mfma_f32_16x16x32_bf16 v[94:97], v[66:69], v[216:219], v[94:97]
	v_mfma_f32_16x16x32_bf16 v[90:93], v[78:81], v[216:219], v[90:93]
	v_mfma_f32_16x16x32_bf16 v[142:145], v[70:73], v[166:169], v[142:145]
	v_mfma_f32_16x16x32_bf16 v[138:141], v[86:89], v[166:169], v[138:141]
	v_mfma_f32_16x16x32_bf16 v[126:129], v[70:73], v[174:177], v[126:129]
	v_mfma_f32_16x16x32_bf16 v[122:125], v[86:89], v[174:177], v[122:125]
	v_mfma_f32_16x16x32_bf16 v[110:113], v[70:73], v[182:185], v[110:113]
	v_mfma_f32_16x16x32_bf16 v[106:109], v[86:89], v[182:185], v[106:109]
	v_mfma_f32_16x16x32_bf16 v[94:97], v[70:73], v[220:223], v[94:97]
	v_mfma_f32_16x16x32_bf16 v[90:93], v[86:89], v[220:223], v[90:93]
	v_mfma_f32_16x16x32_bf16 v[134:137], v[146:149], v[162:165], v[134:137]
	v_mfma_f32_16x16x32_bf16 v[130:133], v[154:157], v[162:165], v[130:133]
	v_mfma_f32_16x16x32_bf16 v[118:121], v[146:149], v[170:173], v[118:121]
	v_mfma_f32_16x16x32_bf16 v[114:117], v[154:157], v[170:173], v[114:117]
	v_mfma_f32_16x16x32_bf16 v[102:105], v[146:149], v[178:181], v[102:105]
	v_mfma_f32_16x16x32_bf16 v[98:101], v[154:157], v[178:181], v[98:101]
	v_mfma_f32_16x16x32_bf16 v[82:85], v[146:149], v[216:219], v[82:85]
	v_mfma_f32_16x16x32_bf16 v[74:77], v[154:157], v[216:219], v[74:77]
	v_mfma_f32_16x16x32_bf16 v[134:137], v[150:153], v[166:169], v[134:137]
	v_mfma_f32_16x16x32_bf16 v[130:133], v[158:161], v[166:169], v[130:133]
	v_mfma_f32_16x16x32_bf16 v[118:121], v[150:153], v[174:177], v[118:121]
	v_mfma_f32_16x16x32_bf16 v[114:117], v[158:161], v[174:177], v[114:117]
	v_mfma_f32_16x16x32_bf16 v[102:105], v[150:153], v[182:185], v[102:105]
	v_mfma_f32_16x16x32_bf16 v[98:101], v[158:161], v[182:185], v[98:101]
	v_mfma_f32_16x16x32_bf16 v[82:85], v[150:153], v[220:223], v[82:85]
	v_mfma_f32_16x16x32_bf16 v[74:77], v[158:161], v[220:223], v[74:77]
	s_barrier
	s_add_i32 s9, s9, s25
	s_mov_b32 m0, s9
	ds_read_b128 v[162:165], v236 offset:49152
	ds_read_b128 v[166:169], v236 offset:50176
	ds_read_b128 v[170:173], v236 offset:51200
	ds_read_b128 v[174:177], v236 offset:52224
	ds_read_b128 v[178:181], v236 offset:53248
	ds_read_b128 v[182:185], v236 offset:54272
	ds_read_b128 v[216:219], v236 offset:55296
	ds_read_b128 v[220:223], v236 offset:56320
	s_add_u32 s100, s46, s60
	s_addc_u32 s101, s47, s61
	global_load_lds_dwordx4 v190, s[100:101]
	s_add_i32 m0, s9, 0x2000
	s_add_u32 s10, s46, 0x20080
	s_addc_u32 s11, s47, 0
	s_add_i32 s9, s12, s25
	global_load_lds_dwordx4 v206, s[100:101]
	s_mov_b32 m0, s9
	s_nop 0
	global_load_lds_dwordx4 v190, s[10:11]
	s_add_i32 m0, s9, 0x2000
	s_nop 0
	global_load_lds_dwordx4 v206, s[10:11]
	s_mov_b32 m0, s75
	s_add_u32 s100, s94, s60
	s_addc_u32 s101, s95, s61
	global_load_lds_dwordx4 v210, s[100:101]
	s_mov_b32 m0, s0
	s_nop 0
	global_load_lds_dwordx4 v208, s[100:101]
	s_waitcnt vmcnt(8)
	s_waitcnt lgkmcnt(0)
	s_barrier
	v_mfma_f32_16x16x32_bf16 v[62:65], v[66:69], v[162:165], v[62:65]
	v_mfma_f32_16x16x32_bf16 v[58:61], v[78:81], v[162:165], v[58:61]
	v_mfma_f32_16x16x32_bf16 v[46:49], v[66:69], v[170:173], v[46:49]
	v_mfma_f32_16x16x32_bf16 v[42:45], v[78:81], v[170:173], v[42:45]
	v_mfma_f32_16x16x32_bf16 v[30:33], v[66:69], v[178:181], v[30:33]
	v_mfma_f32_16x16x32_bf16 v[26:29], v[78:81], v[178:181], v[26:29]
	v_mfma_f32_16x16x32_bf16 v[14:17], v[66:69], v[216:219], v[14:17]
	v_mfma_f32_16x16x32_bf16 v[10:13], v[78:81], v[216:219], v[10:13]
	v_mfma_f32_16x16x32_bf16 v[62:65], v[70:73], v[166:169], v[62:65]
	v_mfma_f32_16x16x32_bf16 v[58:61], v[86:89], v[166:169], v[58:61]
	v_mfma_f32_16x16x32_bf16 v[46:49], v[70:73], v[174:177], v[46:49]
	v_mfma_f32_16x16x32_bf16 v[42:45], v[86:89], v[174:177], v[42:45]
	v_mfma_f32_16x16x32_bf16 v[30:33], v[70:73], v[182:185], v[30:33]
	v_mfma_f32_16x16x32_bf16 v[26:29], v[86:89], v[182:185], v[26:29]
	v_mfma_f32_16x16x32_bf16 v[14:17], v[70:73], v[220:223], v[14:17]
	v_mfma_f32_16x16x32_bf16 v[10:13], v[86:89], v[220:223], v[10:13]
	v_mfma_f32_16x16x32_bf16 v[54:57], v[146:149], v[162:165], v[54:57]
	v_mfma_f32_16x16x32_bf16 v[50:53], v[154:157], v[162:165], v[50:53]
	v_mfma_f32_16x16x32_bf16 v[38:41], v[146:149], v[170:173], v[38:41]
	v_mfma_f32_16x16x32_bf16 v[34:37], v[154:157], v[170:173], v[34:37]
	v_mfma_f32_16x16x32_bf16 v[22:25], v[146:149], v[178:181], v[22:25]
	v_mfma_f32_16x16x32_bf16 v[18:21], v[154:157], v[178:181], v[18:21]
	v_mfma_f32_16x16x32_bf16 v[6:9], v[146:149], v[216:219], v[6:9]
	v_mfma_f32_16x16x32_bf16 v[2:5], v[154:157], v[216:219], v[2:5]
	v_mfma_f32_16x16x32_bf16 v[54:57], v[150:153], v[166:169], v[54:57]
	v_mfma_f32_16x16x32_bf16 v[50:53], v[158:161], v[166:169], v[50:53]
	v_mfma_f32_16x16x32_bf16 v[38:41], v[150:153], v[174:177], v[38:41]
	v_mfma_f32_16x16x32_bf16 v[34:37], v[158:161], v[174:177], v[34:37]
	v_mfma_f32_16x16x32_bf16 v[22:25], v[150:153], v[182:185], v[22:25]
	v_mfma_f32_16x16x32_bf16 v[18:21], v[158:161], v[182:185], v[18:21]
	v_mfma_f32_16x16x32_bf16 v[6:9], v[150:153], v[220:223], v[6:9]
	v_mfma_f32_16x16x32_bf16 v[2:5], v[158:161], v[220:223], v[2:5]
	s_barrier
	s_add_i32 s8, s8, 2
	s_add_u32 s38, s38, 0x100
	s_addc_u32 s39, s39, 0
	s_add_u32 s6, s6, 0x100
	s_addc_u32 s7, s7, 0
	s_cmp_gt_u32 s8, 29
	s_cbranch_scc0 .LBB0_927
	s_and_b64 vcc, exec, s[70:71]
	s_cbranch_vccz .LBB0_930
	s_barrier

; #define PG8_STAGE(bufoff, gbase, voff) do { _Pragma("unroll") for (int _i = 0; _i < 2; ++_i) \
;         __builtin_amdgcn_global_load_lds((const unsigned*)((const char*)(gbase) + (voff)[_i]), (PG8_LAS unsigned*)(lds + (bufoff) + ldsw + _i * 8192), 16, 0, 0); } while (0)
; #define PG8_LDA(dst, b, h) do { _Pragma("unroll") for (int m = 0; m < 4; ++m) _Pragma("unroll") for (int k = 0; k < 2; ++k) dst[m][k] = *(const PG8_LAS bf16x8*)(lds + PG8_SA(b, h) + aoff + m * 2048 + k * 1024); } while (0)
; #define PG8_LDB(dst, b, h) do { _Pragma("unroll") for (int n = 0; n < 2; ++n) _Pragma("unroll") for (int k = 0; k < 2; ++k) dst[n][k] = *(const PG8_LAS bf16x8*)(lds + PG8_SB(b, h) + boff + n * 2048 + k * 1024); } while (0)
; #define PG8_WAIT_V(n) asm volatile("s_waitcnt vmcnt(" #n ")" ::: "memory")
; #define PG8_WAIT_L(n) asm volatile("s_waitcnt lgkmcnt(" #n ")" ::: "memory")
; #define PG8_BAR __builtin_amdgcn_s_barrier()
; #define PG8_SCHED __builtin_amdgcn_sched_barrier(0)
; template <class Epi, class Sched, bool ALIGN_EPI = false, bool SP2 = false>
; __device__ __forceinline__ void gemm_phase(PG8_LAS unsigned char* lds, const Gemm g, const Sched& S, const Epi& E) {
;     ...
;         const bool has_next = S.next(ui + 1, nxt);
;         const char* nA = has_next ? (const char*)g.A + (size_t)nxt.pm * tstep : cA; const char* nB = has_next ? (const char*)g.Bt + (size_t)nxt.pn * tstep : cB;
;         for (int t = 0; t < nt; t += 2) {
;             const bool last = (t == nt - 2);
;             const char* a1 = cA + (size_t)(t + 1) * kstep;
;             const char* a2 = last ? nA : cA + (size_t)(t + 2) * kstep; const char* b2 = last ? nB : cB + (size_t)(t + 2) * kstep;
;             const char* a3 = a2 + kstep; const char* b3 = b2 + kstep;
;             if (last && has_next) S.a_ready(nxt);
;             if constexpr (SP2) {
;             PG8_LDB(B0, 0, 0); PG8_LDB(B1, 0, 1); PG8_SCHED; PG8_LDA(At, 0, 0); PG8_STAGE(PG8_SA(1, 1), a1 + hstep, voffA);
;             PG8_WAIT_V(8); PG8_WAIT_L(0); PG8_BAR; PG8_MMA(0, 0, At, B0); PG8_MMA(0, 1, At, B1); PG8_BAR; PG8_SCHED;
;     ...
; #pragma unroll
;         for (int a = 0; a < 2; ++a)
; #pragma unroll
;             for (int b = 0; b < 2; ++b)
; #pragma unroll
;                 for (int m = 0; m < 4; ++m)
; #pragma unroll
;                     for (int n = 0; n < 2; ++n) acc[a][b][m][n] = (f32x4){0.f, 0.f, 0.f, 0.f};
.LBB0_1070:
	s_ashr_i32 s97, s96, 31
	s_lshl_b64 s[4:5], s[96:97], 22
	s_add_u32 s26, s0, s4
	s_addc_u32 s27, s1, s5
	s_and_b64 s[4:5], s[92:93], exec
	s_cselect_b32 s97, s27, s39
	s_cselect_b32 s4, s26, s38
	s_ashr_i32 s85, s84, 31
	s_lshl_b64 s[6:7], s[84:85], 22
	s_add_u32 s94, s56, s6
	s_addc_u32 s95, s57, s7
	s_and_b64 s[6:7], s[92:93], exec
	s_cselect_b32 s5, s95, s47
	s_cselect_b32 s6, s94, s46
	s_add_u32 s38, s38, 0x200080
	s_addc_u32 s39, s39, 0
	s_add_u32 s7, s46, 0x100
	v_mov_b32_e32 v2, 0
	s_addc_u32 s8, s47, 0
	s_mov_b32 s9, -2
	s_waitcnt lgkmcnt(0)
	v_mov_b32_e32 v3, v2
	v_mov_b32_e32 v4, v2
	v_mov_b32_e32 v5, v2
	v_mov_b32_e32 v6, v2
	v_mov_b32_e32 v7, v2
	v_mov_b32_e32 v8, v2
	v_mov_b32_e32 v9, v2
	v_mov_b32_e32 v18, v2
	v_mov_b32_e32 v19, v2
	v_mov_b32_e32 v20, v2
	v_mov_b32_e32 v21, v2
	v_mov_b32_e32 v22, v2
	v_mov_b32_e32 v23, v2
	v_mov_b32_e32 v24, v2
	v_mov_b32_e32 v25, v2
	v_mov_b32_e32 v34, v2
	v_mov_b32_e32 v35, v2
	v_mov_b32_e32 v36, v2
	v_mov_b32_e32 v37, v2
	v_mov_b32_e32 v38, v2
	v_mov_b32_e32 v39, v2
	v_mov_b32_e32 v40, v2
	v_mov_b32_e32 v41, v2
	v_mov_b32_e32 v50, v2
	v_mov_b32_e32 v51, v2
	v_mov_b32_e32 v52, v2
	v_mov_b32_e32 v53, v2
	v_mov_b32_e32 v54, v2
	v_mov_b32_e32 v55, v2
	v_mov_b32_e32 v56, v2
	v_mov_b32_e32 v57, v2
	v_mov_b32_e32 v10, v2
	v_mov_b32_e32 v11, v2
	v_mov_b32_e32 v12, v2
	v_mov_b32_e32 v13, v2
	v_mov_b32_e32 v14, v2
	v_mov_b32_e32 v15, v2
	v_mov_b32_e32 v16, v2
	v_mov_b32_e32 v17, v2
	v_mov_b32_e32 v26, v2
	v_mov_b32_e32 v27, v2
	v_mov_b32_e32 v28, v2
	v_mov_b32_e32 v29, v2
	v_mov_b32_e32 v30, v2
	v_mov_b32_e32 v31, v2
	v_mov_b32_e32 v32, v2
	v_mov_b32_e32 v33, v2
	v_mov_b32_e32 v42, v2
	v_mov_b32_e32 v43, v2
	v_mov_b32_e32 v44, v2
	v_mov_b32_e32 v45, v2
	v_mov_b32_e32 v46, v2
	v_mov_b32_e32 v47, v2
	v_mov_b32_e32 v48, v2
	v_mov_b32_e32 v49, v2
	v_mov_b32_e32 v58, v2
	v_mov_b32_e32 v59, v2
	v_mov_b32_e32 v60, v2
	v_mov_b32_e32 v61, v2
	v_mov_b32_e32 v62, v2
	v_mov_b32_e32 v63, v2
	v_mov_b32_e32 v64, v2
	v_mov_b32_e32 v65, v2
	v_mov_b32_e32 v66, v2
	v_mov_b32_e32 v67, v2
	v_mov_b32_e32 v68, v2
	v_mov_b32_e32 v69, v2
	v_mov_b32_e32 v70, v2
	v_mov_b32_e32 v71, v2
	v_mov_b32_e32 v72, v2
	v_mov_b32_e32 v73, v2
	v_mov_b32_e32 v82, v2
	v_mov_b32_e32 v83, v2
	v_mov_b32_e32 v84, v2
	v_mov_b32_e32 v85, v2
	v_mov_b32_e32 v86, v2
	v_mov_b32_e32 v87, v2
	v_mov_b32_e32 v88, v2
	v_mov_b32_e32 v89, v2
	v_mov_b32_e32 v98, v2
	v_mov_b32_e32 v99, v2
	v_mov_b32_e32 v100, v2
	v_mov_b32_e32 v101, v2
	v_mov_b32_e32 v102, v2
	v_mov_b32_e32 v103, v2
	v_mov_b32_e32 v104, v2
	v_mov_b32_e32 v105, v2
	v_mov_b32_e32 v114, v2
	v_mov_b32_e32 v115, v2
	v_mov_b32_e32 v116, v2
	v_mov_b32_e32 v117, v2
	v_mov_b32_e32 v118, v2
	v_mov_b32_e32 v119, v2
	v_mov_b32_e32 v120, v2
	v_mov_b32_e32 v121, v2
	v_mov_b32_e32 v74, v2
	v_mov_b32_e32 v75, v2
	v_mov_b32_e32 v76, v2
	v_mov_b32_e32 v77, v2
	v_mov_b32_e32 v78, v2
	v_mov_b32_e32 v79, v2
	v_mov_b32_e32 v80, v2
	v_mov_b32_e32 v81, v2
	v_mov_b32_e32 v90, v2
	v_mov_b32_e32 v91, v2
	v_mov_b32_e32 v92, v2
	v_mov_b32_e32 v93, v2
	v_mov_b32_e32 v94, v2
	v_mov_b32_e32 v95, v2
	v_mov_b32_e32 v96, v2
	v_mov_b32_e32 v97, v2
	v_mov_b32_e32 v106, v2
	v_mov_b32_e32 v107, v2
	v_mov_b32_e32 v108, v2
	v_mov_b32_e32 v109, v2
	v_mov_b32_e32 v110, v2
	v_mov_b32_e32 v111, v2
	v_mov_b32_e32 v112, v2
	v_mov_b32_e32 v113, v2
	v_mov_b32_e32 v122, v2
	v_mov_b32_e32 v123, v2
	v_mov_b32_e32 v124, v2
	v_mov_b32_e32 v125, v2
	v_mov_b32_e32 v126, v2
	v_mov_b32_e32 v127, v2
	v_mov_b32_e32 v128, v2
	v_mov_b32_e32 v129, v2
	v_add_u32_e32 v186, 0x10000, v164
	v_add_u32_e32 v187, 0x14000, v164
	v_add_u32_e32 v198, 0x18000, v164
	v_add_u32_e32 v199, 0x1c000, v164
.LBB0_1071:
	s_add_u32 s10, s38, 0xffe00080
	s_addc_u32 s11, s39, -1
	s_add_i32 s12, 0, 0x10000
	s_cmpk_eq_i32 s9, 0x7c
	s_cselect_b32 vcc_hi, s97, s11
	s_cselect_b32 vcc_lo, s4, s10
	s_cselect_b32 s47, s5, s8
	s_cselect_b32 s46, s6, s7
	s_add_i32 s13, 0, 0x14000
	ds_read_b128 v[130:133], v186
	ds_read_b128 v[134:137], v186 offset:1024
	ds_read_b128 v[138:141], v186 offset:2048
	ds_read_b128 v[152:155], v186 offset:3072
	ds_read_b128 v[156:159], v187
	ds_read_b128 v[160:163], v187 offset:1024
	ds_read_b128 v[168:171], v187 offset:2048
	ds_read_b128 v[172:175], v187 offset:3072
	s_add_i32 m0, s74, 0xc000
	ds_read_b128 v[176:179], v166
	ds_read_b128 v[180:183], v166 offset:1024
	ds_read_b128 v[206:209], v166 offset:2048
	ds_read_b128 v[210:213], v166 offset:3072
	ds_read_b128 v[214:217], v166 offset:4096
	ds_read_b128 v[218:221], v166 offset:5120
	ds_read_b128 v[236:239], v166 offset:6144
	ds_read_b128 v[240:243], v166 offset:7168
	global_load_lds_dwordx4 v148, s[38:39]
	s_add_i32 m0, s74, 0xe000
	s_nop 0
	global_load_lds_dwordx4 v150, s[38:39]
	s_waitcnt vmcnt(8)
	s_waitcnt lgkmcnt(0)
	s_barrier
; #define PG8_STAGE(bufoff, gbase, voff) do { _Pragma("unroll") for (int _i = 0; _i < 2; ++_i) \
;         __builtin_amdgcn_global_load_lds((const unsigned*)((const char*)(gbase) + (voff)[_i]), (PG8_LAS unsigned*)(lds + (bufoff) + ldsw + _i * 8192), 16, 0, 0); } while (0)
; #define PG8_LDA(dst, b, h) do { _Pragma("unroll") for (int m = 0; m < 4; ++m) _Pragma("unroll") for (int k = 0; k < 2; ++k) dst[m][k] = *(const PG8_LAS bf16x8*)(lds + PG8_SA(b, h) + aoff + m * 2048 + k * 1024); } while (0)
; #define PG8_MMA(ai, bj, At, Bt) do { __builtin_amdgcn_s_setprio(1); _Pragma("unroll") for (int m = 0; m < 4; ++m) _Pragma("unroll") for (int n = 0; n < 2; ++n) _Pragma("unroll") for (int k = 0; k < 2; ++k) \
;         acc[ai][bj][m][n] = __builtin_amdgcn_mfma_f32_16x16x32_bf16(Bt[n][k], At[m][k], acc[ai][bj][m][n], 0, 0, 0); __builtin_amdgcn_s_setprio(0); } while (0)
; #define PG8_WAIT_V(n) asm volatile("s_waitcnt vmcnt(" #n ")" ::: "memory")
; #define PG8_WAIT_L(n) asm volatile("s_waitcnt lgkmcnt(" #n ")" ::: "memory")
; #define PG8_BAR __builtin_amdgcn_s_barrier()
; #define PG8_SCHED __builtin_amdgcn_sched_barrier(0)
; template <class Epi, class Sched, bool ALIGN_EPI = false, bool SP2 = false>
; __device__ __forceinline__ void gemm_phase(PG8_LAS unsigned char* lds, const Gemm g, const Sched& S, const Epi& E) {
;     ...
;             PG8_WAIT_V(8); PG8_WAIT_L(0); PG8_BAR; PG8_MMA(0, 0, At, B0); PG8_MMA(0, 1, At, B1); PG8_BAR; PG8_SCHED;
;             PG8_LDA(At, 0, 1); PG8_STAGE(PG8_SB(0, 0), b2, voffB); PG8_STAGE(PG8_SB(0, 1), b2 + hstepB, voffB); PG8_STAGE(PG8_SA(0, 0), a2, voffA);
;             PG8_WAIT_V(8); PG8_WAIT_L(0); PG8_BAR; PG8_MMA(1, 0, At, B0); PG8_MMA(1, 1, At, B1); PG8_BAR; PG8_SCHED;
	v_mfma_f32_16x16x32_bf16 v[126:129], v[130:133], v[176:179], v[126:129]
	v_mfma_f32_16x16x32_bf16 v[122:125], v[138:141], v[176:179], v[122:125]
	v_mfma_f32_16x16x32_bf16 v[110:113], v[130:133], v[206:209], v[110:113]
	v_mfma_f32_16x16x32_bf16 v[106:109], v[138:141], v[206:209], v[106:109]
	v_mfma_f32_16x16x32_bf16 v[94:97], v[130:133], v[214:217], v[94:97]
	v_mfma_f32_16x16x32_bf16 v[90:93], v[138:141], v[214:217], v[90:93]
	v_mfma_f32_16x16x32_bf16 v[78:81], v[130:133], v[236:239], v[78:81]
	v_mfma_f32_16x16x32_bf16 v[74:77], v[138:141], v[236:239], v[74:77]
	v_mfma_f32_16x16x32_bf16 v[126:129], v[134:137], v[180:183], v[126:129]
	v_mfma_f32_16x16x32_bf16 v[122:125], v[152:155], v[180:183], v[122:125]
	v_mfma_f32_16x16x32_bf16 v[110:113], v[134:137], v[210:213], v[110:113]
	v_mfma_f32_16x16x32_bf16 v[106:109], v[152:155], v[210:213], v[106:109]
	v_mfma_f32_16x16x32_bf16 v[94:97], v[134:137], v[218:221], v[94:97]
	v_mfma_f32_16x16x32_bf16 v[90:93], v[152:155], v[218:221], v[90:93]
	v_mfma_f32_16x16x32_bf16 v[78:81], v[134:137], v[240:243], v[78:81]
	v_mfma_f32_16x16x32_bf16 v[74:77], v[152:155], v[240:243], v[74:77]
	v_mfma_f32_16x16x32_bf16 v[118:121], v[156:159], v[176:179], v[118:121]
	v_mfma_f32_16x16x32_bf16 v[114:117], v[168:171], v[176:179], v[114:117]
	v_mfma_f32_16x16x32_bf16 v[102:105], v[156:159], v[206:209], v[102:105]
	v_mfma_f32_16x16x32_bf16 v[98:101], v[168:171], v[206:209], v[98:101]
	v_mfma_f32_16x16x32_bf16 v[86:89], v[156:159], v[214:217], v[86:89]
	v_mfma_f32_16x16x32_bf16 v[82:85], v[168:171], v[214:217], v[82:85]
	v_mfma_f32_16x16x32_bf16 v[70:73], v[156:159], v[236:239], v[70:73]
	v_mfma_f32_16x16x32_bf16 v[66:69], v[168:171], v[236:239], v[66:69]
	v_mfma_f32_16x16x32_bf16 v[118:121], v[160:163], v[180:183], v[118:121]
	v_mfma_f32_16x16x32_bf16 v[114:117], v[172:175], v[180:183], v[114:117]
	v_mfma_f32_16x16x32_bf16 v[102:105], v[160:163], v[210:213], v[102:105]
	v_mfma_f32_16x16x32_bf16 v[98:101], v[172:175], v[210:213], v[98:101]
	v_mfma_f32_16x16x32_bf16 v[86:89], v[160:163], v[218:221], v[86:89]
	v_mfma_f32_16x16x32_bf16 v[82:85], v[172:175], v[218:221], v[82:85]
	v_mfma_f32_16x16x32_bf16 v[70:73], v[160:163], v[240:243], v[70:73]
	v_mfma_f32_16x16x32_bf16 v[66:69], v[172:175], v[240:243], v[66:69]
	s_barrier
	s_add_i32 s10, s12, s67
	s_mov_b32 m0, s10
	ds_read_b128 v[176:179], v166 offset:16384
	ds_read_b128 v[180:183], v166 offset:17408
	ds_read_b128 v[206:209], v166 offset:18432
	ds_read_b128 v[210:213], v166 offset:19456
	ds_read_b128 v[214:217], v166 offset:20480
	ds_read_b128 v[218:221], v166 offset:21504
	ds_read_b128 v[236:239], v166 offset:22528
	ds_read_b128 v[240:243], v166 offset:23552
	global_load_lds_dwordx4 v146, s[46:47]
	s_add_i32 m0, s10, 0x2000
	s_add_u32 s10, s46, 0x80000
	s_addc_u32 s11, s47, 0
	s_add_i32 s12, s13, s67
	global_load_lds_dwordx4 v142, s[46:47]
	s_mov_b32 m0, s12
	s_nop 0
	global_load_lds_dwordx4 v146, s[10:11]
	s_add_i32 m0, s12, 0x2000
	s_nop 0
	global_load_lds_dwordx4 v142, s[10:11]
	s_mov_b32 m0, s74
	s_nop 0
	global_load_lds_dwordx4 v190, vcc
	s_mov_b32 m0, s75
	s_nop 0
	global_load_lds_dwordx4 v144, vcc
	s_waitcnt vmcnt(8)
	s_waitcnt lgkmcnt(0)
	s_barrier
	v_mfma_f32_16x16x32_bf16 v[62:65], v[130:133], v[176:179], v[62:65]
	v_mfma_f32_16x16x32_bf16 v[58:61], v[138:141], v[176:179], v[58:61]
	v_mfma_f32_16x16x32_bf16 v[46:49], v[130:133], v[206:209], v[46:49]
	v_mfma_f32_16x16x32_bf16 v[42:45], v[138:141], v[206:209], v[42:45]
	v_mfma_f32_16x16x32_bf16 v[30:33], v[130:133], v[214:217], v[30:33]
	v_mfma_f32_16x16x32_bf16 v[26:29], v[138:141], v[214:217], v[26:29]
	v_mfma_f32_16x16x32_bf16 v[14:17], v[130:133], v[236:239], v[14:17]
	v_mfma_f32_16x16x32_bf16 v[10:13], v[138:141], v[236:239], v[10:13]
	v_mfma_f32_16x16x32_bf16 v[62:65], v[134:137], v[180:183], v[62:65]
	v_mfma_f32_16x16x32_bf16 v[58:61], v[152:155], v[180:183], v[58:61]
	v_mfma_f32_16x16x32_bf16 v[46:49], v[134:137], v[210:213], v[46:49]
	v_mfma_f32_16x16x32_bf16 v[42:45], v[152:155], v[210:213], v[42:45]
	v_mfma_f32_16x16x32_bf16 v[30:33], v[134:137], v[218:221], v[30:33]
	v_mfma_f32_16x16x32_bf16 v[26:29], v[152:155], v[218:221], v[26:29]
	v_mfma_f32_16x16x32_bf16 v[14:17], v[134:137], v[240:243], v[14:17]
	v_mfma_f32_16x16x32_bf16 v[10:13], v[152:155], v[240:243], v[10:13]
	v_mfma_f32_16x16x32_bf16 v[54:57], v[156:159], v[176:179], v[54:57]
	v_mfma_f32_16x16x32_bf16 v[50:53], v[168:171], v[176:179], v[50:53]
	v_mfma_f32_16x16x32_bf16 v[38:41], v[156:159], v[206:209], v[38:41]
	v_mfma_f32_16x16x32_bf16 v[34:37], v[168:171], v[206:209], v[34:37]
	v_mfma_f32_16x16x32_bf16 v[22:25], v[156:159], v[214:217], v[22:25]
	v_mfma_f32_16x16x32_bf16 v[18:21], v[168:171], v[214:217], v[18:21]
	v_mfma_f32_16x16x32_bf16 v[6:9], v[156:159], v[236:239], v[6:9]
	v_mfma_f32_16x16x32_bf16 v[2:5], v[168:171], v[236:239], v[2:5]
	v_mfma_f32_16x16x32_bf16 v[54:57], v[160:163], v[180:183], v[54:57]
	v_mfma_f32_16x16x32_bf16 v[50:53], v[172:175], v[180:183], v[50:53]
	v_mfma_f32_16x16x32_bf16 v[38:41], v[160:163], v[210:213], v[38:41]
	v_mfma_f32_16x16x32_bf16 v[34:37], v[172:175], v[210:213], v[34:37]
	v_mfma_f32_16x16x32_bf16 v[22:25], v[160:163], v[218:221], v[22:25]
	v_mfma_f32_16x16x32_bf16 v[18:21], v[172:175], v[218:221], v[18:21]
	v_mfma_f32_16x16x32_bf16 v[6:9], v[160:163], v[240:243], v[6:9]
	v_mfma_f32_16x16x32_bf16 v[2:5], v[172:175], v[240:243], v[2:5]
	s_barrier
; #define PG8_STAGE(bufoff, gbase, voff) do { _Pragma("unroll") for (int _i = 0; _i < 2; ++_i) \
;         __builtin_amdgcn_global_load_lds((const unsigned*)((const char*)(gbase) + (voff)[_i]), (PG8_LAS unsigned*)(lds + (bufoff) + ldsw + _i * 8192), 16, 0, 0); } while (0)
; #define PG8_LDA(dst, b, h) do { _Pragma("unroll") for (int m = 0; m < 4; ++m) _Pragma("unroll") for (int k = 0; k < 2; ++k) dst[m][k] = *(const PG8_LAS bf16x8*)(lds + PG8_SA(b, h) + aoff + m * 2048 + k * 1024); } while (0)
; #define PG8_LDB(dst, b, h) do { _Pragma("unroll") for (int n = 0; n < 2; ++n) _Pragma("unroll") for (int k = 0; k < 2; ++k) dst[n][k] = *(const PG8_LAS bf16x8*)(lds + PG8_SB(b, h) + boff + n * 2048 + k * 1024); } while (0)
; #define PG8_MMA(ai, bj, At, Bt) do { __builtin_amdgcn_s_setprio(1); _Pragma("unroll") for (int m = 0; m < 4; ++m) _Pragma("unroll") for (int n = 0; n < 2; ++n) _Pragma("unroll") for (int k = 0; k < 2; ++k) \
;         acc[ai][bj][m][n] = __builtin_amdgcn_mfma_f32_16x16x32_bf16(Bt[n][k], At[m][k], acc[ai][bj][m][n], 0, 0, 0); __builtin_amdgcn_s_setprio(0); } while (0)
; #define PG8_WAIT_V(n) asm volatile("s_waitcnt vmcnt(" #n ")" ::: "memory")
; #define PG8_WAIT_L(n) asm volatile("s_waitcnt lgkmcnt(" #n ")" ::: "memory")
; #define PG8_BAR __builtin_amdgcn_s_barrier()
; #define PG8_SCHED __builtin_amdgcn_sched_barrier(0)
; template <class Epi, class Sched, bool ALIGN_EPI = false, bool SP2 = false>
; __device__ __forceinline__ void gemm_phase(PG8_LAS unsigned char* lds, const Gemm g, const Sched& S, const Epi& E) {
;     ...
;             PG8_LDB(B0, 1, 0); PG8_LDB(B1, 1, 1); PG8_SCHED; PG8_LDA(At, 1, 0); PG8_STAGE(PG8_SA(0, 1), a2 + hstep, voffA);
;             PG8_WAIT_V(8); PG8_WAIT_L(0); PG8_BAR; PG8_MMA(0, 0, At, B0); PG8_MMA(0, 1, At, B1); PG8_BAR; PG8_SCHED;
;             PG8_LDA(At, 1, 1); PG8_STAGE(PG8_SB(1, 0), b3, voffB); PG8_STAGE(PG8_SB(1, 1), b3 + hstepB, voffB); PG8_STAGE(PG8_SA(1, 0), a3, voffA);
;             PG8_WAIT_V(8); PG8_WAIT_L(0); PG8_BAR; PG8_MMA(1, 0, At, B0); PG8_MMA(1, 1, At, B1); PG8_BAR; PG8_SCHED;
	s_add_i32 s12, 0, 0x18000
	s_add_i32 s13, 0, 0x1c000
	ds_read_b128 v[130:133], v198
	ds_read_b128 v[134:137], v198 offset:1024
	ds_read_b128 v[138:141], v198 offset:2048
	ds_read_b128 v[152:155], v198 offset:3072
	ds_read_b128 v[156:159], v199
	ds_read_b128 v[160:163], v199 offset:1024
	ds_read_b128 v[168:171], v199 offset:2048
	ds_read_b128 v[172:175], v199 offset:3072
	s_add_u32 s10, vcc_lo, 0x200000
	s_addc_u32 s11, vcc_hi, 0
	s_mov_b32 m0, s86
	ds_read_b128 v[176:179], v166 offset:32768
	ds_read_b128 v[180:183], v166 offset:33792
	ds_read_b128 v[206:209], v166 offset:34816
	ds_read_b128 v[210:213], v166 offset:35840
	ds_read_b128 v[214:217], v166 offset:36864
	ds_read_b128 v[218:221], v166 offset:37888
	ds_read_b128 v[236:239], v166 offset:38912
	ds_read_b128 v[240:243], v166 offset:39936
	global_load_lds_dwordx4 v190, s[10:11]
	s_mov_b32 m0, s87
	s_nop 0
	global_load_lds_dwordx4 v144, s[10:11]
	s_waitcnt vmcnt(8)
	s_waitcnt lgkmcnt(0)
	s_barrier
	v_mfma_f32_16x16x32_bf16 v[126:129], v[130:133], v[176:179], v[126:129]
	v_mfma_f32_16x16x32_bf16 v[122:125], v[138:141], v[176:179], v[122:125]
	v_mfma_f32_16x16x32_bf16 v[110:113], v[130:133], v[206:209], v[110:113]
	v_mfma_f32_16x16x32_bf16 v[106:109], v[138:141], v[206:209], v[106:109]
	v_mfma_f32_16x16x32_bf16 v[94:97], v[130:133], v[214:217], v[94:97]
	v_mfma_f32_16x16x32_bf16 v[90:93], v[138:141], v[214:217], v[90:93]
	v_mfma_f32_16x16x32_bf16 v[78:81], v[130:133], v[236:239], v[78:81]
	v_mfma_f32_16x16x32_bf16 v[74:77], v[138:141], v[236:239], v[74:77]
	v_mfma_f32_16x16x32_bf16 v[126:129], v[134:137], v[180:183], v[126:129]
	v_mfma_f32_16x16x32_bf16 v[122:125], v[152:155], v[180:183], v[122:125]
	v_mfma_f32_16x16x32_bf16 v[110:113], v[134:137], v[210:213], v[110:113]
	v_mfma_f32_16x16x32_bf16 v[106:109], v[152:155], v[210:213], v[106:109]
	v_mfma_f32_16x16x32_bf16 v[94:97], v[134:137], v[218:221], v[94:97]
	v_mfma_f32_16x16x32_bf16 v[90:93], v[152:155], v[218:221], v[90:93]
	v_mfma_f32_16x16x32_bf16 v[78:81], v[134:137], v[240:243], v[78:81]
	v_mfma_f32_16x16x32_bf16 v[74:77], v[152:155], v[240:243], v[74:77]
	v_mfma_f32_16x16x32_bf16 v[118:121], v[156:159], v[176:179], v[118:121]
	v_mfma_f32_16x16x32_bf16 v[114:117], v[168:171], v[176:179], v[114:117]
	v_mfma_f32_16x16x32_bf16 v[102:105], v[156:159], v[206:209], v[102:105]
	v_mfma_f32_16x16x32_bf16 v[98:101], v[168:171], v[206:209], v[98:101]
	v_mfma_f32_16x16x32_bf16 v[86:89], v[156:159], v[214:217], v[86:89]
	v_mfma_f32_16x16x32_bf16 v[82:85], v[168:171], v[214:217], v[82:85]
	v_mfma_f32_16x16x32_bf16 v[70:73], v[156:159], v[236:239], v[70:73]
	v_mfma_f32_16x16x32_bf16 v[66:69], v[168:171], v[236:239], v[66:69]
	v_mfma_f32_16x16x32_bf16 v[118:121], v[160:163], v[180:183], v[118:121]
	v_mfma_f32_16x16x32_bf16 v[114:117], v[172:175], v[180:183], v[114:117]
	v_mfma_f32_16x16x32_bf16 v[102:105], v[160:163], v[210:213], v[102:105]
	v_mfma_f32_16x16x32_bf16 v[98:101], v[172:175], v[210:213], v[98:101]
	v_mfma_f32_16x16x32_bf16 v[86:89], v[160:163], v[218:221], v[86:89]
	v_mfma_f32_16x16x32_bf16 v[82:85], v[172:175], v[218:221], v[82:85]
	v_mfma_f32_16x16x32_bf16 v[70:73], v[160:163], v[240:243], v[70:73]
	v_mfma_f32_16x16x32_bf16 v[66:69], v[172:175], v[240:243], v[66:69]
	s_barrier
	s_add_i32 s10, s12, s67
	s_mov_b32 m0, s10
	ds_read_b128 v[176:179], v166 offset:49152
	ds_read_b128 v[180:183], v166 offset:50176
	ds_read_b128 v[206:209], v166 offset:51200
	ds_read_b128 v[210:213], v166 offset:52224
	ds_read_b128 v[214:217], v166 offset:53248
	ds_read_b128 v[218:221], v166 offset:54272
	ds_read_b128 v[236:239], v166 offset:55296
	ds_read_b128 v[240:243], v166 offset:56320
	s_add_u32 s100, s46, s60
	s_addc_u32 s101, s47, s61
	global_load_lds_dwordx4 v146, s[100:101]
	s_add_i32 m0, s10, 0x2000
	s_add_u32 s10, s46, 0x80080
	s_addc_u32 s11, s47, 0
	s_add_i32 s12, s13, s67
	global_load_lds_dwordx4 v142, s[100:101]
	s_mov_b32 m0, s12
	s_nop 0
	global_load_lds_dwordx4 v146, s[10:11]
	s_add_i32 m0, s12, 0x2000
	s_nop 0
	global_load_lds_dwordx4 v142, s[10:11]
	s_mov_b32 m0, s82
	s_add_u32 s100, vcc_lo, s60
	s_addc_u32 s101, vcc_hi, s61
	global_load_lds_dwordx4 v190, s[100:101]
	s_mov_b32 m0, s42
	s_nop 0
	global_load_lds_dwordx4 v144, s[100:101]
	s_waitcnt vmcnt(8)
	s_waitcnt lgkmcnt(0)
	s_barrier
	v_mfma_f32_16x16x32_bf16 v[62:65], v[130:133], v[176:179], v[62:65]
	v_mfma_f32_16x16x32_bf16 v[58:61], v[138:141], v[176:179], v[58:61]
	v_mfma_f32_16x16x32_bf16 v[46:49], v[130:133], v[206:209], v[46:49]
	v_mfma_f32_16x16x32_bf16 v[42:45], v[138:141], v[206:209], v[42:45]
	v_mfma_f32_16x16x32_bf16 v[30:33], v[130:133], v[214:217], v[30:33]
	v_mfma_f32_16x16x32_bf16 v[26:29], v[138:141], v[214:217], v[26:29]
	v_mfma_f32_16x16x32_bf16 v[14:17], v[130:133], v[236:239], v[14:17]
	v_mfma_f32_16x16x32_bf16 v[10:13], v[138:141], v[236:239], v[10:13]
	v_mfma_f32_16x16x32_bf16 v[62:65], v[134:137], v[180:183], v[62:65]
	v_mfma_f32_16x16x32_bf16 v[58:61], v[152:155], v[180:183], v[58:61]
	v_mfma_f32_16x16x32_bf16 v[46:49], v[134:137], v[210:213], v[46:49]
	v_mfma_f32_16x16x32_bf16 v[42:45], v[152:155], v[210:213], v[42:45]
	v_mfma_f32_16x16x32_bf16 v[30:33], v[134:137], v[218:221], v[30:33]
	v_mfma_f32_16x16x32_bf16 v[26:29], v[152:155], v[218:221], v[26:29]
	v_mfma_f32_16x16x32_bf16 v[14:17], v[134:137], v[240:243], v[14:17]
	v_mfma_f32_16x16x32_bf16 v[10:13], v[152:155], v[240:243], v[10:13]
	v_mfma_f32_16x16x32_bf16 v[54:57], v[156:159], v[176:179], v[54:57]
	v_mfma_f32_16x16x32_bf16 v[50:53], v[168:171], v[176:179], v[50:53]
	v_mfma_f32_16x16x32_bf16 v[38:41], v[156:159], v[206:209], v[38:41]
	v_mfma_f32_16x16x32_bf16 v[34:37], v[168:171], v[206:209], v[34:37]
	v_mfma_f32_16x16x32_bf16 v[22:25], v[156:159], v[214:217], v[22:25]
	v_mfma_f32_16x16x32_bf16 v[18:21], v[168:171], v[214:217], v[18:21]
	v_mfma_f32_16x16x32_bf16 v[6:9], v[156:159], v[236:239], v[6:9]
	v_mfma_f32_16x16x32_bf16 v[2:5], v[168:171], v[236:239], v[2:5]
	v_mfma_f32_16x16x32_bf16 v[54:57], v[160:163], v[180:183], v[54:57]
	v_mfma_f32_16x16x32_bf16 v[50:53], v[172:175], v[180:183], v[50:53]
	v_mfma_f32_16x16x32_bf16 v[38:41], v[160:163], v[210:213], v[38:41]
	v_mfma_f32_16x16x32_bf16 v[34:37], v[172:175], v[210:213], v[34:37]
	v_mfma_f32_16x16x32_bf16 v[22:25], v[160:163], v[218:221], v[22:25]
	v_mfma_f32_16x16x32_bf16 v[18:21], v[172:175], v[218:221], v[18:21]
	v_mfma_f32_16x16x32_bf16 v[6:9], v[160:163], v[240:243], v[6:9]
	v_mfma_f32_16x16x32_bf16 v[2:5], v[172:175], v[240:243], v[2:5]
	s_barrier
	s_add_i32 s9, s9, 2
	s_add_u32 s38, s38, 0x100
	s_addc_u32 s39, s39, 0
	s_add_u32 s7, s7, 0x100
	s_addc_u32 s8, s8, 0
	s_cmpk_gt_u32 s9, 0x7d
	s_cbranch_scc0 .LBB0_1071
	s_and_b64 vcc, exec, s[72:73]
	s_cbranch_vccz .LBB0_1074
	s_barrier

; #define PG8_STAGE(bufoff, gbase, voff) do { _Pragma("unroll") for (int _i = 0; _i < 2; ++_i) \
;         __builtin_amdgcn_global_load_lds((const unsigned*)((const char*)(gbase) + (voff)[_i]), (PG8_LAS unsigned*)(lds + (bufoff) + ldsw + _i * 8192), 16, 0, 0); } while (0)
; #define PG8_LDA(dst, b, h) do { _Pragma("unroll") for (int m = 0; m < 4; ++m) _Pragma("unroll") for (int k = 0; k < 2; ++k) dst[m][k] = *(const PG8_LAS bf16x8*)(lds + PG8_SA(b, h) + aoff + m * 2048 + k * 1024); } while (0)
; #define PG8_LDB(dst, b, h) do { _Pragma("unroll") for (int n = 0; n < 2; ++n) _Pragma("unroll") for (int k = 0; k < 2; ++k) dst[n][k] = *(const PG8_LAS bf16x8*)(lds + PG8_SB(b, h) + boff + n * 2048 + k * 1024); } while (0)
; #define PG8_WAIT_V(n) asm volatile("s_waitcnt vmcnt(" #n ")" ::: "memory")
; #define PG8_WAIT_L(n) asm volatile("s_waitcnt lgkmcnt(" #n ")" ::: "memory")
; #define PG8_BAR __builtin_amdgcn_s_barrier()
; #define PG8_SCHED __builtin_amdgcn_sched_barrier(0)
; template <class Epi, class Sched, bool ALIGN_EPI = false, bool SP2 = false>
; __device__ __forceinline__ void gemm_phase(PG8_LAS unsigned char* lds, const Gemm g, const Sched& S, const Epi& E) {
;     ...
;         const bool has_next = S.next(ui + 1, nxt);
;         const char* nA = has_next ? (const char*)g.A + (size_t)nxt.pm * tstep : cA; const char* nB = has_next ? (const char*)g.Bt + (size_t)nxt.pn * tstep : cB;
;         for (int t = 0; t < nt; t += 2) {
;             const bool last = (t == nt - 2);
;             const char* a1 = cA + (size_t)(t + 1) * kstep;
;             const char* a2 = last ? nA : cA + (size_t)(t + 2) * kstep; const char* b2 = last ? nB : cB + (size_t)(t + 2) * kstep;
;             const char* a3 = a2 + kstep; const char* b3 = b2 + kstep;
;             if (last && has_next) S.a_ready(nxt);
;             if constexpr (SP2) {
;             PG8_LDB(B0, 0, 0); PG8_LDB(B1, 0, 1); PG8_SCHED; PG8_LDA(At, 0, 0); PG8_STAGE(PG8_SA(1, 1), a1 + hstep, voffA);
;             PG8_WAIT_V(8); PG8_WAIT_L(0); PG8_BAR; PG8_MMA(0, 0, At, B0); PG8_MMA(0, 1, At, B1); PG8_BAR; PG8_SCHED;
;             PG8_LDA(At, 0, 1); PG8_STAGE(PG8_SB(0, 0), b2, voffB); PG8_STAGE(PG8_SB(0, 1), b2 + hstepB, voffB); PG8_STAGE(PG8_SA(0, 0), a2, voffA);
;             PG8_WAIT_V(8); PG8_WAIT_L(0); PG8_BAR; PG8_MMA(1, 0, At, B0); PG8_MMA(1, 1, At, B1); PG8_BAR; PG8_SCHED;
.LBB0_1232:
	s_add_u32 s36, s80, 0x100
	s_addc_u32 s37, s81, 0
	s_ashr_i32 s73, s72, 31
	s_lshl_b64 s[4:5], s[72:73], 20
	s_add_u32 s78, s0, s4
	s_addc_u32 s79, s1, s5
	s_and_b64 s[4:5], s[46:47], exec
	s_cselect_b32 s4, s79, s69
	s_cselect_b32 s5, s78, s68
	s_ashr_i32 s71, s70, 31
	s_lshl_b64 s[6:7], s[70:71], 20
	s_add_u32 s76, s34, s6
	s_addc_u32 s77, s35, s7
	s_and_b64 s[6:7], s[46:47], exec
	s_cselect_b32 s6, s77, s81
	s_cselect_b32 s7, s76, s80
	s_add_u32 s8, s68, 0x80080
	s_addc_u32 s9, s69, 0
	v_lshl_add_u64 v[140:141], s[8:9], 0, v[136:137]
	v_lshl_add_u64 v[142:143], s[8:9], 0, v[138:139]
	s_mov_b32 s8, -2
	s_mov_b64 s[80:81], 0
	v_add_u32_e32 v186, 0x10000, v145
	v_add_u32_e32 v187, 0x14000, v145
	v_add_u32_e32 v198, 0x18000, v145
	v_add_u32_e32 v199, 0x1c000, v145
.LBB0_1233:
	s_add_u32 s9, s68, s80
	s_addc_u32 s10, s69, s81
	s_add_u32 s9, s9, 0x100
	s_addc_u32 s10, s10, 0
	s_add_u32 s100, s9, 0x7ff80
	s_addc_u32 s101, s10, 0
	s_add_u32 s11, s36, s80
	s_addc_u32 s12, s37, s81
	s_add_i32 s13, 0, 0x10000
	s_cmpk_eq_i32 s80, 0xf00
	s_cselect_b32 s93, s4, s10
	s_cselect_b32 s92, s5, s9
	s_cselect_b32 s85, s6, s12
	s_cselect_b32 s84, s7, s11
	s_add_i32 s9, 0, 0x14000
	ds_read_b128 v[152:155], v186
	ds_read_b128 v[156:159], v186 offset:1024
	ds_read_b128 v[160:163], v186 offset:2048
	ds_read_b128 v[164:167], v186 offset:3072
	ds_read_b128 v[168:171], v187
	ds_read_b128 v[172:175], v187 offset:1024
	ds_read_b128 v[176:179], v187 offset:2048
	ds_read_b128 v[180:183], v187 offset:3072
	s_add_i32 m0, s51, 0xc000
	ds_read_b128 v[206:209], v151
	ds_read_b128 v[210:213], v151 offset:1024
	ds_read_b128 v[214:217], v151 offset:2048
	ds_read_b128 v[218:221], v151 offset:3072
	ds_read_b128 v[236:239], v151 offset:4096
	ds_read_b128 v[240:243], v151 offset:5120
	ds_read_b128 v[244:247], v151 offset:6144
	ds_read_b128 v[194:197], v151 offset:7168
	global_load_lds_dwordx4 v136, s[100:101]
	s_add_i32 m0, s51, 0xe000
	s_nop 0
	global_load_lds_dwordx4 v138, s[100:101]
	s_waitcnt vmcnt(8)
	s_waitcnt lgkmcnt(0)
	s_barrier
	v_mfma_f32_16x16x32_bf16 v[126:129], v[152:155], v[206:209], v[126:129]
	v_mfma_f32_16x16x32_bf16 v[122:125], v[160:163], v[206:209], v[122:125]
	v_mfma_f32_16x16x32_bf16 v[118:121], v[152:155], v[214:217], v[118:121]
	v_mfma_f32_16x16x32_bf16 v[114:117], v[160:163], v[214:217], v[114:117]
	v_mfma_f32_16x16x32_bf16 v[110:113], v[152:155], v[236:239], v[110:113]
	v_mfma_f32_16x16x32_bf16 v[106:109], v[160:163], v[236:239], v[106:109]
	v_mfma_f32_16x16x32_bf16 v[102:105], v[152:155], v[244:247], v[102:105]
	v_mfma_f32_16x16x32_bf16 v[98:101], v[160:163], v[244:247], v[98:101]
	v_mfma_f32_16x16x32_bf16 v[126:129], v[156:159], v[210:213], v[126:129]
	v_mfma_f32_16x16x32_bf16 v[122:125], v[164:167], v[210:213], v[122:125]
	v_mfma_f32_16x16x32_bf16 v[118:121], v[156:159], v[218:221], v[118:121]
	v_mfma_f32_16x16x32_bf16 v[114:117], v[164:167], v[218:221], v[114:117]
	v_mfma_f32_16x16x32_bf16 v[110:113], v[156:159], v[240:243], v[110:113]
	v_mfma_f32_16x16x32_bf16 v[106:109], v[164:167], v[240:243], v[106:109]
	v_mfma_f32_16x16x32_bf16 v[102:105], v[156:159], v[194:197], v[102:105]
	v_mfma_f32_16x16x32_bf16 v[98:101], v[164:167], v[194:197], v[98:101]
	v_mfma_f32_16x16x32_bf16 v[94:97], v[168:171], v[206:209], v[94:97]
	v_mfma_f32_16x16x32_bf16 v[90:93], v[176:179], v[206:209], v[90:93]
	v_mfma_f32_16x16x32_bf16 v[86:89], v[168:171], v[214:217], v[86:89]
	v_mfma_f32_16x16x32_bf16 v[82:85], v[176:179], v[214:217], v[82:85]
	v_mfma_f32_16x16x32_bf16 v[78:81], v[168:171], v[236:239], v[78:81]
	v_mfma_f32_16x16x32_bf16 v[74:77], v[176:179], v[236:239], v[74:77]
	v_mfma_f32_16x16x32_bf16 v[70:73], v[168:171], v[244:247], v[70:73]
	v_mfma_f32_16x16x32_bf16 v[66:69], v[176:179], v[244:247], v[66:69]
	v_mfma_f32_16x16x32_bf16 v[94:97], v[172:175], v[210:213], v[94:97]
	v_mfma_f32_16x16x32_bf16 v[90:93], v[180:183], v[210:213], v[90:93]
	v_mfma_f32_16x16x32_bf16 v[86:89], v[172:175], v[218:221], v[86:89]
	v_mfma_f32_16x16x32_bf16 v[82:85], v[180:183], v[218:221], v[82:85]
	v_mfma_f32_16x16x32_bf16 v[78:81], v[172:175], v[240:243], v[78:81]
	v_mfma_f32_16x16x32_bf16 v[74:77], v[180:183], v[240:243], v[74:77]
	v_mfma_f32_16x16x32_bf16 v[70:73], v[172:175], v[194:197], v[70:73]
	v_mfma_f32_16x16x32_bf16 v[66:69], v[180:183], v[194:197], v[66:69]
	s_barrier
	s_add_i32 s10, s13, s42
	s_mov_b32 m0, s10
	ds_read_b128 v[194:197], v151 offset:16384
	ds_read_b128 v[206:209], v151 offset:17408
	ds_read_b128 v[210:213], v151 offset:18432
	ds_read_b128 v[214:217], v151 offset:19456
	ds_read_b128 v[218:221], v151 offset:20480
	ds_read_b128 v[236:239], v151 offset:21504
	ds_read_b128 v[240:243], v151 offset:22528
	ds_read_b128 v[244:247], v151 offset:23552
	global_load_lds_dwordx4 v130, s[84:85]
	s_add_i32 m0, s10, 0x2000
	s_add_u32 s10, s84, 0x20000
	s_addc_u32 s11, s85, 0
	s_add_i32 s9, s9, s42
	global_load_lds_dwordx4 v134, s[84:85]
	s_mov_b32 m0, s9
	s_nop 0
	global_load_lds_dwordx4 v130, s[10:11]
	s_add_i32 m0, s9, 0x2000
	s_nop 0
	global_load_lds_dwordx4 v134, s[10:11]
	s_mov_b32 m0, s51
	s_nop 0
	global_load_lds_dwordx4 v190, s[92:93]
	s_mov_b32 m0, s67
	s_nop 0
	global_load_lds_dwordx4 v132, s[92:93]
	s_waitcnt vmcnt(8)
	s_waitcnt lgkmcnt(0)
	s_barrier
; #define PG8_STAGE(bufoff, gbase, voff) do { _Pragma("unroll") for (int _i = 0; _i < 2; ++_i) \
;         __builtin_amdgcn_global_load_lds((const unsigned*)((const char*)(gbase) + (voff)[_i]), (PG8_LAS unsigned*)(lds + (bufoff) + ldsw + _i * 8192), 16, 0, 0); } while (0)
; #define PG8_LDA(dst, b, h) do { _Pragma("unroll") for (int m = 0; m < 4; ++m) _Pragma("unroll") for (int k = 0; k < 2; ++k) dst[m][k] = *(const PG8_LAS bf16x8*)(lds + PG8_SA(b, h) + aoff + m * 2048 + k * 1024); } while (0)
; #define PG8_LDB(dst, b, h) do { _Pragma("unroll") for (int n = 0; n < 2; ++n) _Pragma("unroll") for (int k = 0; k < 2; ++k) dst[n][k] = *(const PG8_LAS bf16x8*)(lds + PG8_SB(b, h) + boff + n * 2048 + k * 1024); } while (0)
; #define PG8_MMA(ai, bj, At, Bt) do { __builtin_amdgcn_s_setprio(1); _Pragma("unroll") for (int m = 0; m < 4; ++m) _Pragma("unroll") for (int n = 0; n < 2; ++n) _Pragma("unroll") for (int k = 0; k < 2; ++k) \
;         acc[ai][bj][m][n] = __builtin_amdgcn_mfma_f32_16x16x32_bf16(Bt[n][k], At[m][k], acc[ai][bj][m][n], 0, 0, 0); __builtin_amdgcn_s_setprio(0); } while (0)
; #define PG8_WAIT_V(n) asm volatile("s_waitcnt vmcnt(" #n ")" ::: "memory")
; #define PG8_WAIT_L(n) asm volatile("s_waitcnt lgkmcnt(" #n ")" ::: "memory")
; #define PG8_BAR __builtin_amdgcn_s_barrier()
; #define PG8_SCHED __builtin_amdgcn_sched_barrier(0)
; template <class Epi, class Sched, bool ALIGN_EPI = false, bool SP2 = false>
; __device__ __forceinline__ void gemm_phase(PG8_LAS unsigned char* lds, const Gemm g, const Sched& S, const Epi& E) {
;     ...
;             PG8_WAIT_V(8); PG8_WAIT_L(0); PG8_BAR; PG8_MMA(1, 0, At, B0); PG8_MMA(1, 1, At, B1); PG8_BAR; PG8_SCHED;
;             PG8_LDB(B0, 1, 0); PG8_LDB(B1, 1, 1); PG8_SCHED; PG8_LDA(At, 1, 0); PG8_STAGE(PG8_SA(0, 1), a2 + hstep, voffA);
;             PG8_WAIT_V(8); PG8_WAIT_L(0); PG8_BAR; PG8_MMA(0, 0, At, B0); PG8_MMA(0, 1, At, B1); PG8_BAR; PG8_SCHED;
	v_mfma_f32_16x16x32_bf16 v[62:65], v[152:155], v[194:197], v[62:65]
	v_mfma_f32_16x16x32_bf16 v[58:61], v[160:163], v[194:197], v[58:61]
	v_mfma_f32_16x16x32_bf16 v[54:57], v[152:155], v[210:213], v[54:57]
	v_mfma_f32_16x16x32_bf16 v[50:53], v[160:163], v[210:213], v[50:53]
	v_mfma_f32_16x16x32_bf16 v[46:49], v[152:155], v[218:221], v[46:49]
	v_mfma_f32_16x16x32_bf16 v[42:45], v[160:163], v[218:221], v[42:45]
	v_mfma_f32_16x16x32_bf16 v[38:41], v[152:155], v[240:243], v[38:41]
	v_mfma_f32_16x16x32_bf16 v[34:37], v[160:163], v[240:243], v[34:37]
	v_mfma_f32_16x16x32_bf16 v[62:65], v[156:159], v[206:209], v[62:65]
	v_mfma_f32_16x16x32_bf16 v[58:61], v[164:167], v[206:209], v[58:61]
	v_mfma_f32_16x16x32_bf16 v[54:57], v[156:159], v[214:217], v[54:57]
	v_mfma_f32_16x16x32_bf16 v[50:53], v[164:167], v[214:217], v[50:53]
	v_mfma_f32_16x16x32_bf16 v[46:49], v[156:159], v[236:239], v[46:49]
	v_mfma_f32_16x16x32_bf16 v[42:45], v[164:167], v[236:239], v[42:45]
	v_mfma_f32_16x16x32_bf16 v[38:41], v[156:159], v[244:247], v[38:41]
	v_mfma_f32_16x16x32_bf16 v[34:37], v[164:167], v[244:247], v[34:37]
	v_mfma_f32_16x16x32_bf16 v[30:33], v[168:171], v[194:197], v[30:33]
	v_mfma_f32_16x16x32_bf16 v[26:29], v[176:179], v[194:197], v[26:29]
	v_mfma_f32_16x16x32_bf16 v[22:25], v[168:171], v[210:213], v[22:25]
	v_mfma_f32_16x16x32_bf16 v[18:21], v[176:179], v[210:213], v[18:21]
	v_mfma_f32_16x16x32_bf16 v[14:17], v[168:171], v[218:221], v[14:17]
	v_mfma_f32_16x16x32_bf16 v[10:13], v[176:179], v[218:221], v[10:13]
	v_mfma_f32_16x16x32_bf16 v[6:9], v[168:171], v[240:243], v[6:9]
	v_mfma_f32_16x16x32_bf16 v[2:5], v[176:179], v[240:243], v[2:5]
	v_mfma_f32_16x16x32_bf16 v[30:33], v[172:175], v[206:209], v[30:33]
	v_mfma_f32_16x16x32_bf16 v[26:29], v[180:183], v[206:209], v[26:29]
	v_mfma_f32_16x16x32_bf16 v[22:25], v[172:175], v[214:217], v[22:25]
	v_mfma_f32_16x16x32_bf16 v[18:21], v[180:183], v[214:217], v[18:21]
	v_mfma_f32_16x16x32_bf16 v[14:17], v[172:175], v[236:239], v[14:17]
	v_mfma_f32_16x16x32_bf16 v[10:13], v[180:183], v[236:239], v[10:13]
	v_mfma_f32_16x16x32_bf16 v[6:9], v[172:175], v[244:247], v[6:9]
	v_mfma_f32_16x16x32_bf16 v[2:5], v[180:183], v[244:247], v[2:5]
	s_barrier
	s_add_i32 s9, 0, 0x18000
	s_add_i32 s12, 0, 0x1c000
	ds_read_b128 v[152:155], v198
	ds_read_b128 v[156:159], v198 offset:1024
	ds_read_b128 v[160:163], v198 offset:2048
	ds_read_b128 v[164:167], v198 offset:3072
	ds_read_b128 v[168:171], v199
	ds_read_b128 v[172:175], v199 offset:1024
	ds_read_b128 v[176:179], v199 offset:2048
	ds_read_b128 v[180:183], v199 offset:3072
	s_add_u32 s10, s92, 0x80000
	s_addc_u32 s11, s93, 0
	s_mov_b32 m0, s74
	ds_read_b128 v[194:197], v151 offset:32768
	ds_read_b128 v[206:209], v151 offset:33792
	ds_read_b128 v[210:213], v151 offset:34816
	ds_read_b128 v[214:217], v151 offset:35840
	ds_read_b128 v[218:221], v151 offset:36864
	ds_read_b128 v[236:239], v151 offset:37888
	ds_read_b128 v[240:243], v151 offset:38912
	ds_read_b128 v[244:247], v151 offset:39936
	global_load_lds_dwordx4 v190, s[10:11]
	s_mov_b32 m0, s75
	s_nop 0
	global_load_lds_dwordx4 v132, s[10:11]
	s_waitcnt vmcnt(8)
	s_waitcnt lgkmcnt(0)
	s_barrier
	v_mfma_f32_16x16x32_bf16 v[126:129], v[152:155], v[194:197], v[126:129]
	v_mfma_f32_16x16x32_bf16 v[122:125], v[160:163], v[194:197], v[122:125]
	v_mfma_f32_16x16x32_bf16 v[118:121], v[152:155], v[210:213], v[118:121]
	v_mfma_f32_16x16x32_bf16 v[114:117], v[160:163], v[210:213], v[114:117]
	v_mfma_f32_16x16x32_bf16 v[110:113], v[152:155], v[218:221], v[110:113]
	v_mfma_f32_16x16x32_bf16 v[106:109], v[160:163], v[218:221], v[106:109]
	v_mfma_f32_16x16x32_bf16 v[102:105], v[152:155], v[240:243], v[102:105]
	v_mfma_f32_16x16x32_bf16 v[98:101], v[160:163], v[240:243], v[98:101]
	v_mfma_f32_16x16x32_bf16 v[126:129], v[156:159], v[206:209], v[126:129]
	v_mfma_f32_16x16x32_bf16 v[122:125], v[164:167], v[206:209], v[122:125]
	v_mfma_f32_16x16x32_bf16 v[118:121], v[156:159], v[214:217], v[118:121]
	v_mfma_f32_16x16x32_bf16 v[114:117], v[164:167], v[214:217], v[114:117]
	v_mfma_f32_16x16x32_bf16 v[110:113], v[156:159], v[236:239], v[110:113]
	v_mfma_f32_16x16x32_bf16 v[106:109], v[164:167], v[236:239], v[106:109]
	v_mfma_f32_16x16x32_bf16 v[102:105], v[156:159], v[244:247], v[102:105]
	v_mfma_f32_16x16x32_bf16 v[98:101], v[164:167], v[244:247], v[98:101]
	v_mfma_f32_16x16x32_bf16 v[94:97], v[168:171], v[194:197], v[94:97]
	v_mfma_f32_16x16x32_bf16 v[90:93], v[176:179], v[194:197], v[90:93]
	v_mfma_f32_16x16x32_bf16 v[86:89], v[168:171], v[210:213], v[86:89]
	v_mfma_f32_16x16x32_bf16 v[82:85], v[176:179], v[210:213], v[82:85]
	v_mfma_f32_16x16x32_bf16 v[78:81], v[168:171], v[218:221], v[78:81]
	v_mfma_f32_16x16x32_bf16 v[74:77], v[176:179], v[218:221], v[74:77]
	v_mfma_f32_16x16x32_bf16 v[70:73], v[168:171], v[240:243], v[70:73]
	v_mfma_f32_16x16x32_bf16 v[66:69], v[176:179], v[240:243], v[66:69]
	v_mfma_f32_16x16x32_bf16 v[94:97], v[172:175], v[206:209], v[94:97]
	v_mfma_f32_16x16x32_bf16 v[90:93], v[180:183], v[206:209], v[90:93]
	v_mfma_f32_16x16x32_bf16 v[86:89], v[172:175], v[214:217], v[86:89]
	v_mfma_f32_16x16x32_bf16 v[82:85], v[180:183], v[214:217], v[82:85]
	v_mfma_f32_16x16x32_bf16 v[78:81], v[172:175], v[236:239], v[78:81]
	v_mfma_f32_16x16x32_bf16 v[74:77], v[180:183], v[236:239], v[74:77]
	v_mfma_f32_16x16x32_bf16 v[70:73], v[172:175], v[244:247], v[70:73]
	v_mfma_f32_16x16x32_bf16 v[66:69], v[180:183], v[244:247], v[66:69]
	s_barrier
; #define PG8_STAGE(bufoff, gbase, voff) do { _Pragma("unroll") for (int _i = 0; _i < 2; ++_i) \
;         __builtin_amdgcn_global_load_lds((const unsigned*)((const char*)(gbase) + (voff)[_i]), (PG8_LAS unsigned*)(lds + (bufoff) + ldsw + _i * 8192), 16, 0, 0); } while (0)
; #define PG8_LDA(dst, b, h) do { _Pragma("unroll") for (int m = 0; m < 4; ++m) _Pragma("unroll") for (int k = 0; k < 2; ++k) dst[m][k] = *(const PG8_LAS bf16x8*)(lds + PG8_SA(b, h) + aoff + m * 2048 + k * 1024); } while (0)
; #define PG8_MMA(ai, bj, At, Bt) do { __builtin_amdgcn_s_setprio(1); _Pragma("unroll") for (int m = 0; m < 4; ++m) _Pragma("unroll") for (int n = 0; n < 2; ++n) _Pragma("unroll") for (int k = 0; k < 2; ++k) \
;         acc[ai][bj][m][n] = __builtin_amdgcn_mfma_f32_16x16x32_bf16(Bt[n][k], At[m][k], acc[ai][bj][m][n], 0, 0, 0); __builtin_amdgcn_s_setprio(0); } while (0)
; #define PG8_WAIT_V(n) asm volatile("s_waitcnt vmcnt(" #n ")" ::: "memory")
; #define PG8_WAIT_L(n) asm volatile("s_waitcnt lgkmcnt(" #n ")" ::: "memory")
; #define PG8_BAR __builtin_amdgcn_s_barrier()
; #define PG8_SCHED __builtin_amdgcn_sched_barrier(0)
; template <class Epi, class Sched, bool ALIGN_EPI = false, bool SP2 = false>
; __device__ __forceinline__ void gemm_phase(PG8_LAS unsigned char* lds, const Gemm g, const Sched& S, const Epi& E) {
;     ...
;             PG8_LDA(At, 1, 1); PG8_STAGE(PG8_SB(1, 0), b3, voffB); PG8_STAGE(PG8_SB(1, 1), b3 + hstepB, voffB); PG8_STAGE(PG8_SA(1, 0), a3, voffA);
;             PG8_WAIT_V(8); PG8_WAIT_L(0); PG8_BAR; PG8_MMA(1, 0, At, B0); PG8_MMA(1, 1, At, B1); PG8_BAR; PG8_SCHED;
	s_add_i32 s9, s9, s42
	s_mov_b32 m0, s9
	ds_read_b128 v[194:197], v151 offset:49152
	ds_read_b128 v[206:209], v151 offset:50176
	ds_read_b128 v[210:213], v151 offset:51200
	ds_read_b128 v[214:217], v151 offset:52224
	ds_read_b128 v[218:221], v151 offset:53248
	ds_read_b128 v[236:239], v151 offset:54272
	ds_read_b128 v[240:243], v151 offset:55296
	ds_read_b128 v[244:247], v151 offset:56320
	s_add_u32 s100, s84, s60
	s_addc_u32 s101, s85, s61
	global_load_lds_dwordx4 v130, s[100:101]
	s_add_i32 m0, s9, 0x2000
	s_add_u32 s10, s84, 0x20080
	s_addc_u32 s11, s85, 0
	s_add_i32 s9, s12, s42
	global_load_lds_dwordx4 v134, s[100:101]
	s_mov_b32 m0, s9
	s_nop 0
	global_load_lds_dwordx4 v130, s[10:11]
	s_add_i32 m0, s9, 0x2000
	s_nop 0
	global_load_lds_dwordx4 v134, s[10:11]
	s_mov_b32 m0, s82
	s_add_u32 s100, s92, s60
	s_addc_u32 s101, s93, s61
	global_load_lds_dwordx4 v190, s[100:101]
	s_mov_b32 m0, s86
	s_nop 0
	global_load_lds_dwordx4 v132, s[100:101]
	s_waitcnt vmcnt(8)
	s_waitcnt lgkmcnt(0)
	s_barrier
	v_mfma_f32_16x16x32_bf16 v[62:65], v[152:155], v[194:197], v[62:65]
	v_mfma_f32_16x16x32_bf16 v[58:61], v[160:163], v[194:197], v[58:61]
	v_mfma_f32_16x16x32_bf16 v[54:57], v[152:155], v[210:213], v[54:57]
	v_mfma_f32_16x16x32_bf16 v[50:53], v[160:163], v[210:213], v[50:53]
	v_mfma_f32_16x16x32_bf16 v[46:49], v[152:155], v[218:221], v[46:49]
	v_mfma_f32_16x16x32_bf16 v[42:45], v[160:163], v[218:221], v[42:45]
	v_mfma_f32_16x16x32_bf16 v[38:41], v[152:155], v[240:243], v[38:41]
	v_mfma_f32_16x16x32_bf16 v[34:37], v[160:163], v[240:243], v[34:37]
	v_mfma_f32_16x16x32_bf16 v[62:65], v[156:159], v[206:209], v[62:65]
	v_mfma_f32_16x16x32_bf16 v[58:61], v[164:167], v[206:209], v[58:61]
	v_mfma_f32_16x16x32_bf16 v[54:57], v[156:159], v[214:217], v[54:57]
	v_mfma_f32_16x16x32_bf16 v[50:53], v[164:167], v[214:217], v[50:53]
	v_mfma_f32_16x16x32_bf16 v[46:49], v[156:159], v[236:239], v[46:49]
	v_mfma_f32_16x16x32_bf16 v[42:45], v[164:167], v[236:239], v[42:45]
	v_mfma_f32_16x16x32_bf16 v[38:41], v[156:159], v[244:247], v[38:41]
	v_mfma_f32_16x16x32_bf16 v[34:37], v[164:167], v[244:247], v[34:37]
	v_mfma_f32_16x16x32_bf16 v[30:33], v[168:171], v[194:197], v[30:33]
	v_mfma_f32_16x16x32_bf16 v[26:29], v[176:179], v[194:197], v[26:29]
	v_mfma_f32_16x16x32_bf16 v[22:25], v[168:171], v[210:213], v[22:25]
	v_mfma_f32_16x16x32_bf16 v[18:21], v[176:179], v[210:213], v[18:21]
	v_mfma_f32_16x16x32_bf16 v[14:17], v[168:171], v[218:221], v[14:17]
	v_mfma_f32_16x16x32_bf16 v[10:13], v[176:179], v[218:221], v[10:13]
	v_mfma_f32_16x16x32_bf16 v[6:9], v[168:171], v[240:243], v[6:9]
	v_mfma_f32_16x16x32_bf16 v[2:5], v[176:179], v[240:243], v[2:5]
	v_mfma_f32_16x16x32_bf16 v[30:33], v[172:175], v[206:209], v[30:33]
	v_mfma_f32_16x16x32_bf16 v[26:29], v[180:183], v[206:209], v[26:29]
	v_mfma_f32_16x16x32_bf16 v[22:25], v[172:175], v[214:217], v[22:25]
	v_mfma_f32_16x16x32_bf16 v[18:21], v[180:183], v[214:217], v[18:21]
	v_mfma_f32_16x16x32_bf16 v[14:17], v[172:175], v[236:239], v[14:17]
	v_mfma_f32_16x16x32_bf16 v[10:13], v[180:183], v[236:239], v[10:13]
	v_mfma_f32_16x16x32_bf16 v[6:9], v[172:175], v[244:247], v[6:9]
	v_mfma_f32_16x16x32_bf16 v[2:5], v[180:183], v[244:247], v[2:5]
	s_barrier
	s_add_i32 s8, s8, 2
	s_add_u32 s80, s80, 0x100
	s_addc_u32 s81, s81, 0
	s_cmp_gt_u32 s8, 29
	s_cbranch_scc0 .LBB0_1233
	s_and_b64 vcc, exec, s[62:63]
	s_cbranch_vccz .LBB0_1236
	s_barrier
